# conversion load re-balanced: scan slices convert mats 11,13,15,17,27,22,23; idle tails use the streamlined converter with explicit lists (R1: 24,28; L1 GU: 25,26,30; L2 GU: 29,31) so that each fits un
# baseline (speedup 1.0000x reference)
; #define GAS __attribute__((address_space(1)))
; #define LAS __attribute__((address_space(3)))
; __device__ __forceinline__ void conv_load(const float* W, int K, int N, int Np, int item, int lane, f32x4 (&v)[2][8]) {
;     const int nblk = Np / 64, kb = item / nblk, nb = item % nblk, k0 = 64 * kb, n0 = 64 * nb;
;     const int kr = lane >> 3, n4 = lane & 7;
; #pragma unroll
;     for (int hf = 0; hf < 2; ++hf)
; #pragma unroll
;         for (int i = 0; i < 8; ++i) { const int k = k0 + 8 * i + kr, n = n0 + 32 * hf + 4 * n4;
;             v[hf][i] = (k < K && n < N) ? __builtin_nontemporal_load((const GAS f32x4*)(W + (size_t)k * N + n)) : (f32x4){0.f, 0.f, 0.f, 0.f}; }
; }
; __device__ __forceinline__ void convert_mats(Frame& F, int m_lo, int m_hi, int gw, int NGW) {
;     LAS float* scr = (LAS float*)(F.lds + F.wave * 16384);
;     int it = gw, base = 0;
;     for (int mi = m_lo; mi < m_hi; ++mi) {
;         const MatI mt = kMats[mi]; const int cnt = (mt.Kp / 64) * (mt.Np / 64);
;         const float* src = in_ptr(F, mt.in_idx) + mt.src_off; const float* gain = mt.gain_idx >= 0 ? in_ptr(F, mt.gain_idx) + mt.gain_off : nullptr; bf16* dst = (bf16*)((unsigned char*)in_ptr(F, T_WS) + mt.dst_off);
;         while (it < base + cnt) {
;             f32x4 va[2][8], vb[2][8];
;             const int lim = base + cnt, i1 = it + NGW;
;             conv_load(src, mt.K, mt.N, mt.Np, it - base, F.lane, va);
;             if (i1 < lim) conv_load(src, mt.K, mt.N, mt.Np, i1 - base, F.lane, vb);
;             conv_proc(va, gain, mt.K, mt.Kp, mt.Np, mt.ilv, dst, scr, it - base, F.lane);
;             if (i1 < lim) conv_proc(vb, gain, mt.K, mt.Kp, mt.Np, mt.ilv, dst, scr, i1 - base, F.lane);
;             it = (i1 < lim) ? i1 + NGW : i1;
;         }
.LBB0_1332:
	s_and_b64 vcc, exec, s[0:1]
	s_cbranch_vccz .LBB0_1449
	s_sub_i32 s0, s2, s33
	s_cmp_lt_i32 s0, 0
	s_mov_b32 s39, 0
	s_cbranch_scc1 .LBB0_1449
	s_mov_b32 s33, s0
	v_mbcnt_lo_u32_b32 v182, -1, 0
	v_mbcnt_hi_u32_b32 v182, -1, v182
	v_lshrrev_b32_e32 v183, 3, v182
	v_and_b32_e32 v184, 7, v182
	s_lshl_b32 s4, s80, 14
	v_mul_u32_u24_e32 v0, 132, v183
	v_lshl_add_u32 v0, v184, 4, v0
	v_add_u32_e32 v172, s4, v0
	v_add_u32_e32 v173, 0x420, v172
	v_add_u32_e32 v174, 0x840, v172
	v_add_u32_e32 v175, 0xc60, v172
	v_add_u32_e32 v176, 0x1080, v172
	v_add_u32_e32 v177, 0x14a0, v172
	v_add_u32_e32 v178, 0x18c0, v172
	v_add_u32_e32 v179, 0x1ce0, v172
	v_mul_u32_u24_e32 v0, 0x420, v184
	v_lshl_add_u32 v0, v183, 2, v0
	v_add_u32_e32 v180, s4, v0
	v_lshlrev_b32_e32 v181, 2, v183
	s_lshl_b32 s20, s33, 3
	s_add_u32 s20, s20, s80
	s_lshl_b32 s21, s3, 3
	s_mov_b32 s22, 0
	s_add_i32 s4, 0, 0x20520
	v_mov_b32_e32 v0, s4
	ds_read_b64 v[2:3], v0
	s_waitcnt lgkmcnt(0)
	s_nop 0
	v_readfirstlane_b32 s58, v2
	v_readfirstlane_b32 s59, v3
	s_add_u32 s23, s22, 0x1600
	s_cmp_ge_u32 s20, s23
	s_cbranch_scc1 .Lcvb_m24_done
	s_add_i32 s4, 0, 0x204d8
	v_mov_b32_e32 v0, s4
	ds_read_b64 v[2:3], v0
	s_waitcnt lgkmcnt(0)
	s_nop 0
	v_readfirstlane_b32 s24, v2
	v_readfirstlane_b32 s25, v3
	s_add_u32 s24, s24, 0xb000000
	s_addc_u32 s25, s25, 0
	s_add_i32 s4, 0, 0x204d0
	v_mov_b32_e32 v0, s4
	ds_read_b64 v[2:3], v0
	s_waitcnt lgkmcnt(0)
	s_nop 0
	v_readfirstlane_b32 s26, v2
	v_readfirstlane_b32 s27, v3
	s_add_u32 s26, s26, 0x4000
	s_addc_u32 s27, s27, 0
	s_add_u32 s28, s58, 0x13f00000
	s_addc_u32 s29, s59, 0
	s_mov_b32 s30, 0xb000
	s_mov_b32 s31, 0x1000
	s_mov_b32 s34, 0x1745d18
	s_mov_b32 s35, 176
	s_mov_b32 s36, 5632
	v_mul_lo_u32 v0, v183, s30
	v_lshl_add_u32 v160, v184, 4, v0
	v_add_u32_e32 v161, 0x58000, v160
	v_add_u32_e32 v162, 0xb0000, v160
	v_add_u32_e32 v163, 0x108000, v160
	v_add_u32_e32 v164, 0x160000, v160
	v_add_u32_e32 v165, 0x1b8000, v160
	v_add_u32_e32 v166, 0x210000, v160
	v_add_u32_e32 v167, 0x268000, v160
	v_mul_lo_u32 v0, v183, s31
	v_lshl_add_u32 v168, v184, 4, v0
	v_add_u32_e32 v169, 0x8000, v168
	v_add_u32_e32 v170, 0x10000, v168
	v_add_u32_e32 v171, 0x18000, v168
.Lcvb_m24_loop:
	s_sub_u32 s10, s20, s22
	s_mul_hi_u32 s4, s10, s34
	s_mul_i32 s5, s4, s35
	s_sub_u32 s5, s10, s5
	s_lshl_b32 s6, s30, 6
	s_mul_i32 s6, s6, s4
	s_lshl_b32 s7, s5, 8
	s_add_u32 s6, s6, s7
	s_add_u32 s38, s24, s6
	s_addc_u32 s39, s25, 0
	s_lshl_b32 s6, s4, 8
	s_add_u32 s40, s26, s6
	s_addc_u32 s41, s27, 0
	s_lshl_b32 s7, s5, 6
	s_cmp_eq_u32 s36, 0
	s_cbranch_scc1 .Lcvb_noilv0
	s_cmp_ge_u32 s7, s36
	s_cselect_b32 s8, s36, 0
	s_cselect_b32 s9, 128, 0
	s_sub_u32 s7, s7, s8
	s_lshr_b32 s8, s7, 7
	s_lshl_b32 s8, s8, 8
	s_and_b32 s7, s7, 127
	s_add_u32 s7, s7, s8
	s_add_u32 s7, s7, s9
.Lcvb_noilv0:
	s_mul_i32 s7, s7, s31
	s_lshl_b32 s6, s4, 7
	s_add_u32 s7, s7, s6
	s_add_u32 s42, s28, s7
	s_addc_u32 s43, s29, 0
	s_lshl_b32 s6, s31, 5
	s_add_u32 s44, s42, s6
	s_addc_u32 s45, s43, 0
	s_add_u32 s11, s20, s21
	s_cmp_lt_u32 s11, s23
	s_cselect_b32 s60, 1, 0
	s_cbranch_scc0 .Lcvb_m24_oneitem
	s_sub_u32 s10, s11, s22
	s_mul_hi_u32 s4, s10, s34
	s_mul_i32 s5, s4, s35
	s_sub_u32 s5, s10, s5
	s_lshl_b32 s6, s30, 6
	s_mul_i32 s6, s6, s4
	s_lshl_b32 s7, s5, 8
	s_add_u32 s6, s6, s7
	s_add_u32 s46, s24, s6
	s_addc_u32 s47, s25, 0
	s_lshl_b32 s6, s4, 8
	s_add_u32 s48, s26, s6
	s_addc_u32 s49, s27, 0
	s_lshl_b32 s7, s5, 6
	s_cmp_eq_u32 s36, 0
	s_cbranch_scc1 .Lcvb_noilv1
	s_cmp_ge_u32 s7, s36
	s_cselect_b32 s8, s36, 0
	s_cselect_b32 s9, 128, 0
	s_sub_u32 s7, s7, s8
	s_lshr_b32 s8, s7, 7
	s_lshl_b32 s8, s8, 8
	s_and_b32 s7, s7, 127
	s_add_u32 s7, s7, s8
	s_add_u32 s7, s7, s9
.Lcvb_noilv1:
	s_mul_i32 s7, s7, s31
	s_lshl_b32 s6, s4, 7
	s_add_u32 s7, s7, s6
	s_add_u32 s50, s28, s7
	s_addc_u32 s51, s29, 0
	s_lshl_b32 s6, s31, 5
	s_add_u32 s54, s50, s6
	s_addc_u32 s55, s51, 0
	global_load_dwordx4 v[16:19], v160, s[38:39] nt
	global_load_dwordx4 v[20:23], v161, s[38:39] nt
	global_load_dwordx4 v[24:27], v162, s[38:39] nt
	global_load_dwordx4 v[28:31], v163, s[38:39] nt
	global_load_dwordx4 v[32:35], v164, s[38:39] nt
	global_load_dwordx4 v[36:39], v165, s[38:39] nt
	global_load_dwordx4 v[40:43], v166, s[38:39] nt
	global_load_dwordx4 v[44:47], v167, s[38:39] nt
	global_load_dwordx4 v[48:51], v160, s[38:39] offset:128 nt
	global_load_dwordx4 v[52:55], v161, s[38:39] offset:128 nt
	global_load_dwordx4 v[56:59], v162, s[38:39] offset:128 nt
	global_load_dwordx4 v[60:63], v163, s[38:39] offset:128 nt
	global_load_dwordx4 v[64:67], v164, s[38:39] offset:128 nt
	global_load_dwordx4 v[68:71], v165, s[38:39] offset:128 nt
	global_load_dwordx4 v[72:75], v166, s[38:39] offset:128 nt
	global_load_dwordx4 v[76:79], v167, s[38:39] offset:128 nt
	global_load_dword v144, v181, s[40:41]
	global_load_dword v145, v181, s[40:41] offset:32
	global_load_dword v146, v181, s[40:41] offset:64
	global_load_dword v147, v181, s[40:41] offset:96
	global_load_dword v148, v181, s[40:41] offset:128
	global_load_dword v149, v181, s[40:41] offset:160
	global_load_dword v150, v181, s[40:41] offset:192
	global_load_dword v151, v181, s[40:41] offset:224
	global_load_dwordx4 v[80:83], v160, s[46:47] nt
	global_load_dwordx4 v[84:87], v161, s[46:47] nt
	global_load_dwordx4 v[88:91], v162, s[46:47] nt
	global_load_dwordx4 v[92:95], v163, s[46:47] nt
	global_load_dwordx4 v[96:99], v164, s[46:47] nt
	global_load_dwordx4 v[100:103], v165, s[46:47] nt
	global_load_dwordx4 v[104:107], v166, s[46:47] nt
	global_load_dwordx4 v[108:111], v167, s[46:47] nt
	global_load_dwordx4 v[112:115], v160, s[46:47] offset:128 nt
	global_load_dwordx4 v[116:119], v161, s[46:47] offset:128 nt
	global_load_dwordx4 v[120:123], v162, s[46:47] offset:128 nt
	global_load_dwordx4 v[124:127], v163, s[46:47] offset:128 nt
	global_load_dwordx4 v[128:131], v164, s[46:47] offset:128 nt
	global_load_dwordx4 v[132:135], v165, s[46:47] offset:128 nt
	global_load_dwordx4 v[136:139], v166, s[46:47] offset:128 nt
	global_load_dwordx4 v[140:143], v167, s[46:47] offset:128 nt
	global_load_dword v152, v181, s[48:49]
	global_load_dword v153, v181, s[48:49] offset:32
	global_load_dword v154, v181, s[48:49] offset:64
	global_load_dword v155, v181, s[48:49] offset:96
	global_load_dword v156, v181, s[48:49] offset:128
	global_load_dword v157, v181, s[48:49] offset:160
	global_load_dword v158, v181, s[48:49] offset:192
	global_load_dword v159, v181, s[48:49] offset:224
	s_waitcnt vmcnt(24)
; #define GAS __attribute__((address_space(1)))
; #define LAS __attribute__((address_space(3)))
; #define LDS_WAIT() asm volatile("s_waitcnt lgkmcnt(0)" ::: "memory")
; __device__ __forceinline__ unsigned pk2(float lo, float hi) { unsigned r; asm("v_cvt_pk_bf16_f32 %0, %1, %2" : "=v"(r) : "v"(lo), "v"(hi)); return r; }
; __device__ __forceinline__ void conv_proc(f32x4 (&v)[2][8], const float* gain, int K, int Kp, int Np, int ilv, bf16* WT, LAS float* scr, int item, int lane) {
;     const int nblk = Np / 64, kb = item / nblk, nb = item % nblk, k0 = 64 * kb, n0 = 64 * nb;
;     const int d0 = ilv ? (((n0 % ilv) >> 7) * 256 + (n0 / ilv) * 128 + ((n0 % ilv) & 127)) : n0;
;     const int kr = lane >> 3, n4 = lane & 7;
;     if (gain) {
; #pragma unroll
;         for (int i = 0; i < 8; ++i) { const int k = k0 + 8 * i + kr; const float g = k < K ? gain[k] : 0.f; v[0][i] *= g; v[1][i] *= g; } }
;     const int c = lane & 7;
; #pragma unroll
;     for (int hf = 0; hf < 2; ++hf) {
; #pragma unroll
;         for (int i = 0; i < 8; ++i) { LAS float* d = scr + (8 * i + kr) * 33 + 4 * n4; d[0] = v[hf][i][0]; d[1] = v[hf][i][1]; d[2] = v[hf][i][2]; d[3] = v[hf][i][3]; }
;         LDS_WAIT(); asm volatile("" ::: "memory");
; #pragma unroll
;         for (int j = 0; j < 4; ++j) { const int nn = (lane >> 3) + 8 * j; const LAS float* sp = scr + (8 * c) * 33 + nn;
;             v4u o; o.x = pk2(sp[0 * 33], sp[1 * 33]); o.y = pk2(sp[2 * 33], sp[3 * 33]); o.z = pk2(sp[4 * 33], sp[5 * 33]); o.w = pk2(sp[6 * 33], sp[7 * 33]);
;             __builtin_nontemporal_store(o, (GAS v4u*)(WT + (size_t)(d0 + 32 * hf + nn) * Kp + k0 + 8 * c)); }
;         LDS_WAIT(); asm volatile("" ::: "memory");
;     }
; }
	v_pk_mul_f32 v[16:17], v[16:17], v[144:145] op_sel_hi:[1,0]
	v_pk_mul_f32 v[18:19], v[18:19], v[144:145] op_sel_hi:[1,0]
	v_pk_mul_f32 v[20:21], v[20:21], v[144:145] op_sel:[0,1] op_sel_hi:[1,1]
	v_pk_mul_f32 v[22:23], v[22:23], v[144:145] op_sel:[0,1] op_sel_hi:[1,1]
	v_pk_mul_f32 v[24:25], v[24:25], v[146:147] op_sel_hi:[1,0]
	v_pk_mul_f32 v[26:27], v[26:27], v[146:147] op_sel_hi:[1,0]
	v_pk_mul_f32 v[28:29], v[28:29], v[146:147] op_sel:[0,1] op_sel_hi:[1,1]
	v_pk_mul_f32 v[30:31], v[30:31], v[146:147] op_sel:[0,1] op_sel_hi:[1,1]
	v_pk_mul_f32 v[32:33], v[32:33], v[148:149] op_sel_hi:[1,0]
	v_pk_mul_f32 v[34:35], v[34:35], v[148:149] op_sel_hi:[1,0]
	v_pk_mul_f32 v[36:37], v[36:37], v[148:149] op_sel:[0,1] op_sel_hi:[1,1]
	v_pk_mul_f32 v[38:39], v[38:39], v[148:149] op_sel:[0,1] op_sel_hi:[1,1]
	v_pk_mul_f32 v[40:41], v[40:41], v[150:151] op_sel_hi:[1,0]
	v_pk_mul_f32 v[42:43], v[42:43], v[150:151] op_sel_hi:[1,0]
	v_pk_mul_f32 v[44:45], v[44:45], v[150:151] op_sel:[0,1] op_sel_hi:[1,1]
	v_pk_mul_f32 v[46:47], v[46:47], v[150:151] op_sel:[0,1] op_sel_hi:[1,1]
	v_pk_mul_f32 v[48:49], v[48:49], v[144:145] op_sel_hi:[1,0]
	v_pk_mul_f32 v[50:51], v[50:51], v[144:145] op_sel_hi:[1,0]
	v_pk_mul_f32 v[52:53], v[52:53], v[144:145] op_sel:[0,1] op_sel_hi:[1,1]
	v_pk_mul_f32 v[54:55], v[54:55], v[144:145] op_sel:[0,1] op_sel_hi:[1,1]
	v_pk_mul_f32 v[56:57], v[56:57], v[146:147] op_sel_hi:[1,0]
	v_pk_mul_f32 v[58:59], v[58:59], v[146:147] op_sel_hi:[1,0]
	v_pk_mul_f32 v[60:61], v[60:61], v[146:147] op_sel:[0,1] op_sel_hi:[1,1]
	v_pk_mul_f32 v[62:63], v[62:63], v[146:147] op_sel:[0,1] op_sel_hi:[1,1]
	v_pk_mul_f32 v[64:65], v[64:65], v[148:149] op_sel_hi:[1,0]
	v_pk_mul_f32 v[66:67], v[66:67], v[148:149] op_sel_hi:[1,0]
	v_pk_mul_f32 v[68:69], v[68:69], v[148:149] op_sel:[0,1] op_sel_hi:[1,1]
	v_pk_mul_f32 v[70:71], v[70:71], v[148:149] op_sel:[0,1] op_sel_hi:[1,1]
	v_pk_mul_f32 v[72:73], v[72:73], v[150:151] op_sel_hi:[1,0]
	v_pk_mul_f32 v[74:75], v[74:75], v[150:151] op_sel_hi:[1,0]
	v_pk_mul_f32 v[76:77], v[76:77], v[150:151] op_sel:[0,1] op_sel_hi:[1,1]
	v_pk_mul_f32 v[78:79], v[78:79], v[150:151] op_sel:[0,1] op_sel_hi:[1,1]
	ds_write2_b32 v172, v16, v17 offset1:1
	ds_write2_b32 v172, v18, v19 offset0:2 offset1:3
	ds_write2_b32 v173, v20, v21 offset1:1
	ds_write2_b32 v173, v22, v23 offset0:2 offset1:3
	ds_write2_b32 v174, v24, v25 offset1:1
	ds_write2_b32 v174, v26, v27 offset0:2 offset1:3
	ds_write2_b32 v175, v28, v29 offset1:1
	ds_write2_b32 v175, v30, v31 offset0:2 offset1:3
	ds_write2_b32 v176, v32, v33 offset1:1
	ds_write2_b32 v176, v34, v35 offset0:2 offset1:3
	ds_write2_b32 v177, v36, v37 offset1:1
	ds_write2_b32 v177, v38, v39 offset0:2 offset1:3
	ds_write2_b32 v178, v40, v41 offset1:1
	ds_write2_b32 v178, v42, v43 offset0:2 offset1:3
	ds_write2_b32 v179, v44, v45 offset1:1
	ds_write2_b32 v179, v46, v47 offset0:2 offset1:3
	s_waitcnt lgkmcnt(0)
	ds_read2_b32 v[0:1], v180 offset0:0 offset1:33
	ds_read2_b32 v[2:3], v180 offset0:66 offset1:99
	ds_read2_b32 v[4:5], v180 offset0:132 offset1:165
	ds_read2_b32 v[6:7], v180 offset0:198 offset1:231
	ds_read2_b32 v[8:9], v180 offset0:8 offset1:41
	ds_read2_b32 v[10:11], v180 offset0:74 offset1:107
	ds_read2_b32 v[12:13], v180 offset0:140 offset1:173
	ds_read2_b32 v[14:15], v180 offset0:206 offset1:239
	s_waitcnt lgkmcnt(4)
	v_cvt_pk_bf16_f32 v186, v0, v1
	v_cvt_pk_bf16_f32 v187, v2, v3
	v_cvt_pk_bf16_f32 v188, v4, v5
	v_cvt_pk_bf16_f32 v189, v6, v7
	global_store_dwordx4 v168, v[186:189], s[42:43] nt
	ds_read2_b32 v[0:1], v180 offset0:16 offset1:49
	ds_read2_b32 v[2:3], v180 offset0:82 offset1:115
	ds_read2_b32 v[4:5], v180 offset0:148 offset1:181
	ds_read2_b32 v[6:7], v180 offset0:214 offset1:247
	s_waitcnt lgkmcnt(4)
	v_cvt_pk_bf16_f32 v190, v8, v9
	v_cvt_pk_bf16_f32 v191, v10, v11
	v_cvt_pk_bf16_f32 v192, v12, v13
	v_cvt_pk_bf16_f32 v193, v14, v15
	global_store_dwordx4 v169, v[190:193], s[42:43] nt
	ds_read2_b32 v[8:9], v180 offset0:24 offset1:57
	ds_read2_b32 v[10:11], v180 offset0:90 offset1:123
	ds_read2_b32 v[12:13], v180 offset0:156 offset1:189
	ds_read2_b32 v[14:15], v180 offset0:222 offset1:255
	s_waitcnt lgkmcnt(4)
	v_cvt_pk_bf16_f32 v186, v0, v1
	v_cvt_pk_bf16_f32 v187, v2, v3
	v_cvt_pk_bf16_f32 v188, v4, v5
	v_cvt_pk_bf16_f32 v189, v6, v7
	global_store_dwordx4 v170, v[186:189], s[42:43] nt
	s_waitcnt lgkmcnt(0)
	v_cvt_pk_bf16_f32 v190, v8, v9
	v_cvt_pk_bf16_f32 v191, v10, v11
	v_cvt_pk_bf16_f32 v192, v12, v13
	v_cvt_pk_bf16_f32 v193, v14, v15
	global_store_dwordx4 v171, v[190:193], s[42:43] nt
	ds_write2_b32 v172, v48, v49 offset1:1
	ds_write2_b32 v172, v50, v51 offset0:2 offset1:3
	ds_write2_b32 v173, v52, v53 offset1:1
	ds_write2_b32 v173, v54, v55 offset0:2 offset1:3
	ds_write2_b32 v174, v56, v57 offset1:1
	ds_write2_b32 v174, v58, v59 offset0:2 offset1:3
	ds_write2_b32 v175, v60, v61 offset1:1
	ds_write2_b32 v175, v62, v63 offset0:2 offset1:3
	ds_write2_b32 v176, v64, v65 offset1:1
	ds_write2_b32 v176, v66, v67 offset0:2 offset1:3
	ds_write2_b32 v177, v68, v69 offset1:1
	ds_write2_b32 v177, v70, v71 offset0:2 offset1:3
	ds_write2_b32 v178, v72, v73 offset1:1
	ds_write2_b32 v178, v74, v75 offset0:2 offset1:3
	ds_write2_b32 v179, v76, v77 offset1:1
	ds_write2_b32 v179, v78, v79 offset0:2 offset1:3
	s_waitcnt lgkmcnt(0)
	ds_read2_b32 v[0:1], v180 offset0:0 offset1:33
	ds_read2_b32 v[2:3], v180 offset0:66 offset1:99
	ds_read2_b32 v[4:5], v180 offset0:132 offset1:165
	ds_read2_b32 v[6:7], v180 offset0:198 offset1:231
	ds_read2_b32 v[8:9], v180 offset0:8 offset1:41
	ds_read2_b32 v[10:11], v180 offset0:74 offset1:107
	ds_read2_b32 v[12:13], v180 offset0:140 offset1:173
	ds_read2_b32 v[14:15], v180 offset0:206 offset1:239
	s_waitcnt lgkmcnt(4)
; #define GAS __attribute__((address_space(1)))
; #define LAS __attribute__((address_space(3)))
; #define LDS_WAIT() asm volatile("s_waitcnt lgkmcnt(0)" ::: "memory")
; __device__ __forceinline__ unsigned pk2(float lo, float hi) { unsigned r; asm("v_cvt_pk_bf16_f32 %0, %1, %2" : "=v"(r) : "v"(lo), "v"(hi)); return r; }
; __device__ __forceinline__ void conv_proc(f32x4 (&v)[2][8], const float* gain, int K, int Kp, int Np, int ilv, bf16* WT, LAS float* scr, int item, int lane) {
;     const int nblk = Np / 64, kb = item / nblk, nb = item % nblk, k0 = 64 * kb, n0 = 64 * nb;
;     const int d0 = ilv ? (((n0 % ilv) >> 7) * 256 + (n0 / ilv) * 128 + ((n0 % ilv) & 127)) : n0;
;     const int kr = lane >> 3, n4 = lane & 7;
;     if (gain) {
; #pragma unroll
;         for (int i = 0; i < 8; ++i) { const int k = k0 + 8 * i + kr; const float g = k < K ? gain[k] : 0.f; v[0][i] *= g; v[1][i] *= g; } }
;     const int c = lane & 7;
; #pragma unroll
;     for (int hf = 0; hf < 2; ++hf) {
; #pragma unroll
;         for (int i = 0; i < 8; ++i) { LAS float* d = scr + (8 * i + kr) * 33 + 4 * n4; d[0] = v[hf][i][0]; d[1] = v[hf][i][1]; d[2] = v[hf][i][2]; d[3] = v[hf][i][3]; }
;         LDS_WAIT(); asm volatile("" ::: "memory");
; #pragma unroll
;         for (int j = 0; j < 4; ++j) { const int nn = (lane >> 3) + 8 * j; const LAS float* sp = scr + (8 * c) * 33 + nn;
;             v4u o; o.x = pk2(sp[0 * 33], sp[1 * 33]); o.y = pk2(sp[2 * 33], sp[3 * 33]); o.z = pk2(sp[4 * 33], sp[5 * 33]); o.w = pk2(sp[6 * 33], sp[7 * 33]);
;             __builtin_nontemporal_store(o, (GAS v4u*)(WT + (size_t)(d0 + 32 * hf + nn) * Kp + k0 + 8 * c)); }
;         LDS_WAIT(); asm volatile("" ::: "memory");
;     }
; }
	v_cvt_pk_bf16_f32 v186, v0, v1
	v_cvt_pk_bf16_f32 v187, v2, v3
	v_cvt_pk_bf16_f32 v188, v4, v5
	v_cvt_pk_bf16_f32 v189, v6, v7
	global_store_dwordx4 v168, v[186:189], s[44:45] nt
	ds_read2_b32 v[0:1], v180 offset0:16 offset1:49
	ds_read2_b32 v[2:3], v180 offset0:82 offset1:115
	ds_read2_b32 v[4:5], v180 offset0:148 offset1:181
	ds_read2_b32 v[6:7], v180 offset0:214 offset1:247
	s_waitcnt lgkmcnt(4)
	v_cvt_pk_bf16_f32 v190, v8, v9
	v_cvt_pk_bf16_f32 v191, v10, v11
	v_cvt_pk_bf16_f32 v192, v12, v13
	v_cvt_pk_bf16_f32 v193, v14, v15
	global_store_dwordx4 v169, v[190:193], s[44:45] nt
	ds_read2_b32 v[8:9], v180 offset0:24 offset1:57
	ds_read2_b32 v[10:11], v180 offset0:90 offset1:123
	ds_read2_b32 v[12:13], v180 offset0:156 offset1:189
	ds_read2_b32 v[14:15], v180 offset0:222 offset1:255
	s_waitcnt lgkmcnt(4)
	v_cvt_pk_bf16_f32 v186, v0, v1
	v_cvt_pk_bf16_f32 v187, v2, v3
	v_cvt_pk_bf16_f32 v188, v4, v5
	v_cvt_pk_bf16_f32 v189, v6, v7
	global_store_dwordx4 v170, v[186:189], s[44:45] nt
	s_waitcnt lgkmcnt(0)
	v_cvt_pk_bf16_f32 v190, v8, v9
	v_cvt_pk_bf16_f32 v191, v10, v11
	v_cvt_pk_bf16_f32 v192, v12, v13
	v_cvt_pk_bf16_f32 v193, v14, v15
	global_store_dwordx4 v171, v[190:193], s[44:45] nt
	s_waitcnt vmcnt(8)
	v_pk_mul_f32 v[80:81], v[80:81], v[152:153] op_sel_hi:[1,0]
	v_pk_mul_f32 v[82:83], v[82:83], v[152:153] op_sel_hi:[1,0]
	v_pk_mul_f32 v[84:85], v[84:85], v[152:153] op_sel:[0,1] op_sel_hi:[1,1]
	v_pk_mul_f32 v[86:87], v[86:87], v[152:153] op_sel:[0,1] op_sel_hi:[1,1]
	v_pk_mul_f32 v[88:89], v[88:89], v[154:155] op_sel_hi:[1,0]
	v_pk_mul_f32 v[90:91], v[90:91], v[154:155] op_sel_hi:[1,0]
	v_pk_mul_f32 v[92:93], v[92:93], v[154:155] op_sel:[0,1] op_sel_hi:[1,1]
	v_pk_mul_f32 v[94:95], v[94:95], v[154:155] op_sel:[0,1] op_sel_hi:[1,1]
	v_pk_mul_f32 v[96:97], v[96:97], v[156:157] op_sel_hi:[1,0]
	v_pk_mul_f32 v[98:99], v[98:99], v[156:157] op_sel_hi:[1,0]
	v_pk_mul_f32 v[100:101], v[100:101], v[156:157] op_sel:[0,1] op_sel_hi:[1,1]
	v_pk_mul_f32 v[102:103], v[102:103], v[156:157] op_sel:[0,1] op_sel_hi:[1,1]
	v_pk_mul_f32 v[104:105], v[104:105], v[158:159] op_sel_hi:[1,0]
	v_pk_mul_f32 v[106:107], v[106:107], v[158:159] op_sel_hi:[1,0]
	v_pk_mul_f32 v[108:109], v[108:109], v[158:159] op_sel:[0,1] op_sel_hi:[1,1]
	v_pk_mul_f32 v[110:111], v[110:111], v[158:159] op_sel:[0,1] op_sel_hi:[1,1]
	v_pk_mul_f32 v[112:113], v[112:113], v[152:153] op_sel_hi:[1,0]
	v_pk_mul_f32 v[114:115], v[114:115], v[152:153] op_sel_hi:[1,0]
	v_pk_mul_f32 v[116:117], v[116:117], v[152:153] op_sel:[0,1] op_sel_hi:[1,1]
	v_pk_mul_f32 v[118:119], v[118:119], v[152:153] op_sel:[0,1] op_sel_hi:[1,1]
	v_pk_mul_f32 v[120:121], v[120:121], v[154:155] op_sel_hi:[1,0]
	v_pk_mul_f32 v[122:123], v[122:123], v[154:155] op_sel_hi:[1,0]
	v_pk_mul_f32 v[124:125], v[124:125], v[154:155] op_sel:[0,1] op_sel_hi:[1,1]
	v_pk_mul_f32 v[126:127], v[126:127], v[154:155] op_sel:[0,1] op_sel_hi:[1,1]
	v_pk_mul_f32 v[128:129], v[128:129], v[156:157] op_sel_hi:[1,0]
	v_pk_mul_f32 v[130:131], v[130:131], v[156:157] op_sel_hi:[1,0]
	v_pk_mul_f32 v[132:133], v[132:133], v[156:157] op_sel:[0,1] op_sel_hi:[1,1]
	v_pk_mul_f32 v[134:135], v[134:135], v[156:157] op_sel:[0,1] op_sel_hi:[1,1]
	v_pk_mul_f32 v[136:137], v[136:137], v[158:159] op_sel_hi:[1,0]
	v_pk_mul_f32 v[138:139], v[138:139], v[158:159] op_sel_hi:[1,0]
	v_pk_mul_f32 v[140:141], v[140:141], v[158:159] op_sel:[0,1] op_sel_hi:[1,1]
	v_pk_mul_f32 v[142:143], v[142:143], v[158:159] op_sel:[0,1] op_sel_hi:[1,1]
	ds_write2_b32 v172, v80, v81 offset1:1
	ds_write2_b32 v172, v82, v83 offset0:2 offset1:3
	ds_write2_b32 v173, v84, v85 offset1:1
	ds_write2_b32 v173, v86, v87 offset0:2 offset1:3
	ds_write2_b32 v174, v88, v89 offset1:1
	ds_write2_b32 v174, v90, v91 offset0:2 offset1:3
	ds_write2_b32 v175, v92, v93 offset1:1
	ds_write2_b32 v175, v94, v95 offset0:2 offset1:3
	ds_write2_b32 v176, v96, v97 offset1:1
	ds_write2_b32 v176, v98, v99 offset0:2 offset1:3
	ds_write2_b32 v177, v100, v101 offset1:1
	ds_write2_b32 v177, v102, v103 offset0:2 offset1:3
	ds_write2_b32 v178, v104, v105 offset1:1
	ds_write2_b32 v178, v106, v107 offset0:2 offset1:3
	ds_write2_b32 v179, v108, v109 offset1:1
	ds_write2_b32 v179, v110, v111 offset0:2 offset1:3
	s_waitcnt lgkmcnt(0)
	ds_read2_b32 v[0:1], v180 offset0:0 offset1:33
	ds_read2_b32 v[2:3], v180 offset0:66 offset1:99
	ds_read2_b32 v[4:5], v180 offset0:132 offset1:165
	ds_read2_b32 v[6:7], v180 offset0:198 offset1:231
	ds_read2_b32 v[8:9], v180 offset0:8 offset1:41
	ds_read2_b32 v[10:11], v180 offset0:74 offset1:107
	ds_read2_b32 v[12:13], v180 offset0:140 offset1:173
	ds_read2_b32 v[14:15], v180 offset0:206 offset1:239
	s_waitcnt lgkmcnt(4)
	v_cvt_pk_bf16_f32 v186, v0, v1
	v_cvt_pk_bf16_f32 v187, v2, v3
	v_cvt_pk_bf16_f32 v188, v4, v5
	v_cvt_pk_bf16_f32 v189, v6, v7
	global_store_dwordx4 v168, v[186:189], s[50:51] nt
	ds_read2_b32 v[0:1], v180 offset0:16 offset1:49
	ds_read2_b32 v[2:3], v180 offset0:82 offset1:115
	ds_read2_b32 v[4:5], v180 offset0:148 offset1:181
	ds_read2_b32 v[6:7], v180 offset0:214 offset1:247
	s_waitcnt lgkmcnt(4)
	v_cvt_pk_bf16_f32 v190, v8, v9
	v_cvt_pk_bf16_f32 v191, v10, v11
	v_cvt_pk_bf16_f32 v192, v12, v13
	v_cvt_pk_bf16_f32 v193, v14, v15
	global_store_dwordx4 v169, v[190:193], s[50:51] nt
	ds_read2_b32 v[8:9], v180 offset0:24 offset1:57
	ds_read2_b32 v[10:11], v180 offset0:90 offset1:123
	ds_read2_b32 v[12:13], v180 offset0:156 offset1:189
	ds_read2_b32 v[14:15], v180 offset0:222 offset1:255
	s_waitcnt lgkmcnt(4)
	v_cvt_pk_bf16_f32 v186, v0, v1
	v_cvt_pk_bf16_f32 v187, v2, v3
	v_cvt_pk_bf16_f32 v188, v4, v5
	v_cvt_pk_bf16_f32 v189, v6, v7
	global_store_dwordx4 v170, v[186:189], s[50:51] nt
	s_waitcnt lgkmcnt(0)
; #define GAS __attribute__((address_space(1)))
; #define LAS __attribute__((address_space(3)))
; __device__ __forceinline__ void conv_proc(f32x4 (&v)[2][8], const float* gain, int K, int Kp, int Np, int ilv, bf16* WT, LAS float* scr, int item, int lane) {
;     const int nblk = Np / 64, kb = item / nblk, nb = item % nblk, k0 = 64 * kb, n0 = 64 * nb;
;     const int d0 = ilv ? (((n0 % ilv) >> 7) * 256 + (n0 / ilv) * 128 + ((n0 % ilv) & 127)) : n0;
;     const int kr = lane >> 3, n4 = lane & 7;
;     if (gain) {
; #pragma unroll
;         for (int i = 0; i < 8; ++i) { const int k = k0 + 8 * i + kr; const float g = k < K ? gain[k] : 0.f; v[0][i] *= g; v[1][i] *= g; } }
;     const int c = lane & 7;
; #pragma unroll
;     for (int hf = 0; hf < 2; ++hf) {
; #pragma unroll
;         for (int i = 0; i < 8; ++i) { LAS float* d = scr + (8 * i + kr) * 33 + 4 * n4; d[0] = v[hf][i][0]; d[1] = v[hf][i][1]; d[2] = v[hf][i][2]; d[3] = v[hf][i][3]; }
;         LDS_WAIT(); asm volatile("" ::: "memory");
; #pragma unroll
;         for (int j = 0; j < 4; ++j) { const int nn = (lane >> 3) + 8 * j; const LAS float* sp = scr + (8 * c) * 33 + nn;
;             v4u o; o.x = pk2(sp[0 * 33], sp[1 * 33]); o.y = pk2(sp[2 * 33], sp[3 * 33]); o.z = pk2(sp[4 * 33], sp[5 * 33]); o.w = pk2(sp[6 * 33], sp[7 * 33]);
;             __builtin_nontemporal_store(o, (GAS v4u*)(WT + (size_t)(d0 + 32 * hf + nn) * Kp + k0 + 8 * c)); }
;         LDS_WAIT(); asm volatile("" ::: "memory");
;     }
; }
; __device__ __forceinline__ void convert_mats(Frame& F, int m_lo, int m_hi, int gw, int NGW) {
;     LAS float* scr = (LAS float*)(F.lds + F.wave * 16384);
;     int it = gw, base = 0;
;     for (int mi = m_lo; mi < m_hi; ++mi) {
;         const MatI mt = kMats[mi]; const int cnt = (mt.Kp / 64) * (mt.Np / 64);
;         const float* src = in_ptr(F, mt.in_idx) + mt.src_off; const float* gain = mt.gain_idx >= 0 ? in_ptr(F, mt.gain_idx) + mt.gain_off : nullptr; bf16* dst = (bf16*)((unsigned char*)in_ptr(F, T_WS) + mt.dst_off);
;         while (it < base + cnt) {
;             f32x4 va[2][8], vb[2][8];
;             const int lim = base + cnt, i1 = it + NGW;
;             conv_load(src, mt.K, mt.N, mt.Np, it - base, F.lane, va);
;             if (i1 < lim) conv_load(src, mt.K, mt.N, mt.Np, i1 - base, F.lane, vb);
;             conv_proc(va, gain, mt.K, mt.Kp, mt.Np, mt.ilv, dst, scr, it - base, F.lane);
	v_cvt_pk_bf16_f32 v190, v8, v9
	v_cvt_pk_bf16_f32 v191, v10, v11
	v_cvt_pk_bf16_f32 v192, v12, v13
	v_cvt_pk_bf16_f32 v193, v14, v15
	global_store_dwordx4 v171, v[190:193], s[50:51] nt
	ds_write2_b32 v172, v112, v113 offset1:1
	ds_write2_b32 v172, v114, v115 offset0:2 offset1:3
	ds_write2_b32 v173, v116, v117 offset1:1
	ds_write2_b32 v173, v118, v119 offset0:2 offset1:3
	ds_write2_b32 v174, v120, v121 offset1:1
	ds_write2_b32 v174, v122, v123 offset0:2 offset1:3
	ds_write2_b32 v175, v124, v125 offset1:1
	ds_write2_b32 v175, v126, v127 offset0:2 offset1:3
	ds_write2_b32 v176, v128, v129 offset1:1
	ds_write2_b32 v176, v130, v131 offset0:2 offset1:3
	ds_write2_b32 v177, v132, v133 offset1:1
	ds_write2_b32 v177, v134, v135 offset0:2 offset1:3
	ds_write2_b32 v178, v136, v137 offset1:1
	ds_write2_b32 v178, v138, v139 offset0:2 offset1:3
	ds_write2_b32 v179, v140, v141 offset1:1
	ds_write2_b32 v179, v142, v143 offset0:2 offset1:3
	s_waitcnt lgkmcnt(0)
	ds_read2_b32 v[0:1], v180 offset0:0 offset1:33
	ds_read2_b32 v[2:3], v180 offset0:66 offset1:99
	ds_read2_b32 v[4:5], v180 offset0:132 offset1:165
	ds_read2_b32 v[6:7], v180 offset0:198 offset1:231
	ds_read2_b32 v[8:9], v180 offset0:8 offset1:41
	ds_read2_b32 v[10:11], v180 offset0:74 offset1:107
	ds_read2_b32 v[12:13], v180 offset0:140 offset1:173
	ds_read2_b32 v[14:15], v180 offset0:206 offset1:239
	s_waitcnt lgkmcnt(4)
	v_cvt_pk_bf16_f32 v186, v0, v1
	v_cvt_pk_bf16_f32 v187, v2, v3
	v_cvt_pk_bf16_f32 v188, v4, v5
	v_cvt_pk_bf16_f32 v189, v6, v7
	global_store_dwordx4 v168, v[186:189], s[54:55] nt
	ds_read2_b32 v[0:1], v180 offset0:16 offset1:49
	ds_read2_b32 v[2:3], v180 offset0:82 offset1:115
	ds_read2_b32 v[4:5], v180 offset0:148 offset1:181
	ds_read2_b32 v[6:7], v180 offset0:214 offset1:247
	s_waitcnt lgkmcnt(4)
	v_cvt_pk_bf16_f32 v190, v8, v9
	v_cvt_pk_bf16_f32 v191, v10, v11
	v_cvt_pk_bf16_f32 v192, v12, v13
	v_cvt_pk_bf16_f32 v193, v14, v15
	global_store_dwordx4 v169, v[190:193], s[54:55] nt
	ds_read2_b32 v[8:9], v180 offset0:24 offset1:57
	ds_read2_b32 v[10:11], v180 offset0:90 offset1:123
	ds_read2_b32 v[12:13], v180 offset0:156 offset1:189
	ds_read2_b32 v[14:15], v180 offset0:222 offset1:255
	s_waitcnt lgkmcnt(4)
	v_cvt_pk_bf16_f32 v186, v0, v1
	v_cvt_pk_bf16_f32 v187, v2, v3
	v_cvt_pk_bf16_f32 v188, v4, v5
	v_cvt_pk_bf16_f32 v189, v6, v7
	global_store_dwordx4 v170, v[186:189], s[54:55] nt
	s_waitcnt lgkmcnt(0)
	v_cvt_pk_bf16_f32 v190, v8, v9
	v_cvt_pk_bf16_f32 v191, v10, v11
	v_cvt_pk_bf16_f32 v192, v12, v13
	v_cvt_pk_bf16_f32 v193, v14, v15
	global_store_dwordx4 v171, v[190:193], s[54:55] nt
	s_lshl_b32 s4, s21, 1
	s_add_u32 s20, s20, s4
	s_cmp_lt_u32 s20, s23
	s_cbranch_scc1 .Lcvb_m24_loop
	s_branch .Lcvb_m24_done
.Lcvb_m24_oneitem:
	global_load_dwordx4 v[16:19], v160, s[38:39] nt
	global_load_dwordx4 v[20:23], v161, s[38:39] nt
	global_load_dwordx4 v[24:27], v162, s[38:39] nt
	global_load_dwordx4 v[28:31], v163, s[38:39] nt
	global_load_dwordx4 v[32:35], v164, s[38:39] nt
	global_load_dwordx4 v[36:39], v165, s[38:39] nt
	global_load_dwordx4 v[40:43], v166, s[38:39] nt
	global_load_dwordx4 v[44:47], v167, s[38:39] nt
	global_load_dwordx4 v[48:51], v160, s[38:39] offset:128 nt
	global_load_dwordx4 v[52:55], v161, s[38:39] offset:128 nt
	global_load_dwordx4 v[56:59], v162, s[38:39] offset:128 nt
	global_load_dwordx4 v[60:63], v163, s[38:39] offset:128 nt
	global_load_dwordx4 v[64:67], v164, s[38:39] offset:128 nt
	global_load_dwordx4 v[68:71], v165, s[38:39] offset:128 nt
	global_load_dwordx4 v[72:75], v166, s[38:39] offset:128 nt
	global_load_dwordx4 v[76:79], v167, s[38:39] offset:128 nt
	global_load_dword v144, v181, s[40:41]
	global_load_dword v145, v181, s[40:41] offset:32
	global_load_dword v146, v181, s[40:41] offset:64
	global_load_dword v147, v181, s[40:41] offset:96
	global_load_dword v148, v181, s[40:41] offset:128
	global_load_dword v149, v181, s[40:41] offset:160
	global_load_dword v150, v181, s[40:41] offset:192
	global_load_dword v151, v181, s[40:41] offset:224
	s_waitcnt vmcnt(0)
	v_pk_mul_f32 v[16:17], v[16:17], v[144:145] op_sel_hi:[1,0]
	v_pk_mul_f32 v[18:19], v[18:19], v[144:145] op_sel_hi:[1,0]
	v_pk_mul_f32 v[20:21], v[20:21], v[144:145] op_sel:[0,1] op_sel_hi:[1,1]
	v_pk_mul_f32 v[22:23], v[22:23], v[144:145] op_sel:[0,1] op_sel_hi:[1,1]
	v_pk_mul_f32 v[24:25], v[24:25], v[146:147] op_sel_hi:[1,0]
	v_pk_mul_f32 v[26:27], v[26:27], v[146:147] op_sel_hi:[1,0]
	v_pk_mul_f32 v[28:29], v[28:29], v[146:147] op_sel:[0,1] op_sel_hi:[1,1]
	v_pk_mul_f32 v[30:31], v[30:31], v[146:147] op_sel:[0,1] op_sel_hi:[1,1]
	v_pk_mul_f32 v[32:33], v[32:33], v[148:149] op_sel_hi:[1,0]
	v_pk_mul_f32 v[34:35], v[34:35], v[148:149] op_sel_hi:[1,0]
	v_pk_mul_f32 v[36:37], v[36:37], v[148:149] op_sel:[0,1] op_sel_hi:[1,1]
	v_pk_mul_f32 v[38:39], v[38:39], v[148:149] op_sel:[0,1] op_sel_hi:[1,1]
	v_pk_mul_f32 v[40:41], v[40:41], v[150:151] op_sel_hi:[1,0]
	v_pk_mul_f32 v[42:43], v[42:43], v[150:151] op_sel_hi:[1,0]
	v_pk_mul_f32 v[44:45], v[44:45], v[150:151] op_sel:[0,1] op_sel_hi:[1,1]
	v_pk_mul_f32 v[46:47], v[46:47], v[150:151] op_sel:[0,1] op_sel_hi:[1,1]
	v_pk_mul_f32 v[48:49], v[48:49], v[144:145] op_sel_hi:[1,0]
	v_pk_mul_f32 v[50:51], v[50:51], v[144:145] op_sel_hi:[1,0]
	v_pk_mul_f32 v[52:53], v[52:53], v[144:145] op_sel:[0,1] op_sel_hi:[1,1]
	v_pk_mul_f32 v[54:55], v[54:55], v[144:145] op_sel:[0,1] op_sel_hi:[1,1]
	v_pk_mul_f32 v[56:57], v[56:57], v[146:147] op_sel_hi:[1,0]
	v_pk_mul_f32 v[58:59], v[58:59], v[146:147] op_sel_hi:[1,0]
	v_pk_mul_f32 v[60:61], v[60:61], v[146:147] op_sel:[0,1] op_sel_hi:[1,1]
	v_pk_mul_f32 v[62:63], v[62:63], v[146:147] op_sel:[0,1] op_sel_hi:[1,1]
	v_pk_mul_f32 v[64:65], v[64:65], v[148:149] op_sel_hi:[1,0]
	v_pk_mul_f32 v[66:67], v[66:67], v[148:149] op_sel_hi:[1,0]
	v_pk_mul_f32 v[68:69], v[68:69], v[148:149] op_sel:[0,1] op_sel_hi:[1,1]
	v_pk_mul_f32 v[70:71], v[70:71], v[148:149] op_sel:[0,1] op_sel_hi:[1,1]
	v_pk_mul_f32 v[72:73], v[72:73], v[150:151] op_sel_hi:[1,0]
	v_pk_mul_f32 v[74:75], v[74:75], v[150:151] op_sel_hi:[1,0]
	v_pk_mul_f32 v[76:77], v[76:77], v[150:151] op_sel:[0,1] op_sel_hi:[1,1]
	v_pk_mul_f32 v[78:79], v[78:79], v[150:151] op_sel:[0,1] op_sel_hi:[1,1]
	ds_write2_b32 v172, v16, v17 offset1:1
	ds_write2_b32 v172, v18, v19 offset0:2 offset1:3
	ds_write2_b32 v173, v20, v21 offset1:1
	ds_write2_b32 v173, v22, v23 offset0:2 offset1:3
	ds_write2_b32 v174, v24, v25 offset1:1
	ds_write2_b32 v174, v26, v27 offset0:2 offset1:3
	ds_write2_b32 v175, v28, v29 offset1:1
	ds_write2_b32 v175, v30, v31 offset0:2 offset1:3
	ds_write2_b32 v176, v32, v33 offset1:1
	ds_write2_b32 v176, v34, v35 offset0:2 offset1:3
	ds_write2_b32 v177, v36, v37 offset1:1
	ds_write2_b32 v177, v38, v39 offset0:2 offset1:3
	ds_write2_b32 v178, v40, v41 offset1:1
	ds_write2_b32 v178, v42, v43 offset0:2 offset1:3
	ds_write2_b32 v179, v44, v45 offset1:1
	ds_write2_b32 v179, v46, v47 offset0:2 offset1:3
	s_waitcnt lgkmcnt(0)
; #define GAS __attribute__((address_space(1)))
; #define LAS __attribute__((address_space(3)))
; #define LDS_WAIT() asm volatile("s_waitcnt lgkmcnt(0)" ::: "memory")
; __device__ __forceinline__ unsigned pk2(float lo, float hi) { unsigned r; asm("v_cvt_pk_bf16_f32 %0, %1, %2" : "=v"(r) : "v"(lo), "v"(hi)); return r; }
; __device__ __forceinline__ void conv_proc(f32x4 (&v)[2][8], const float* gain, int K, int Kp, int Np, int ilv, bf16* WT, LAS float* scr, int item, int lane) {
;     const int nblk = Np / 64, kb = item / nblk, nb = item % nblk, k0 = 64 * kb, n0 = 64 * nb;
;     const int d0 = ilv ? (((n0 % ilv) >> 7) * 256 + (n0 / ilv) * 128 + ((n0 % ilv) & 127)) : n0;
;     const int kr = lane >> 3, n4 = lane & 7;
;     if (gain) {
; #pragma unroll
;         for (int i = 0; i < 8; ++i) { const int k = k0 + 8 * i + kr; const float g = k < K ? gain[k] : 0.f; v[0][i] *= g; v[1][i] *= g; } }
;     const int c = lane & 7;
; #pragma unroll
;     for (int hf = 0; hf < 2; ++hf) {
; #pragma unroll
;         for (int i = 0; i < 8; ++i) { LAS float* d = scr + (8 * i + kr) * 33 + 4 * n4; d[0] = v[hf][i][0]; d[1] = v[hf][i][1]; d[2] = v[hf][i][2]; d[3] = v[hf][i][3]; }
;         LDS_WAIT(); asm volatile("" ::: "memory");
; #pragma unroll
;         for (int j = 0; j < 4; ++j) { const int nn = (lane >> 3) + 8 * j; const LAS float* sp = scr + (8 * c) * 33 + nn;
;             v4u o; o.x = pk2(sp[0 * 33], sp[1 * 33]); o.y = pk2(sp[2 * 33], sp[3 * 33]); o.z = pk2(sp[4 * 33], sp[5 * 33]); o.w = pk2(sp[6 * 33], sp[7 * 33]);
;             __builtin_nontemporal_store(o, (GAS v4u*)(WT + (size_t)(d0 + 32 * hf + nn) * Kp + k0 + 8 * c)); }
;         LDS_WAIT(); asm volatile("" ::: "memory");
;     }
; }
; __device__ __forceinline__ void convert_mats(Frame& F, int m_lo, int m_hi, int gw, int NGW) {
;     ...
;     for (int mi = m_lo; mi < m_hi; ++mi) {
;         const MatI mt = kMats[mi]; const int cnt = (mt.Kp / 64) * (mt.Np / 64);
;         const float* src = in_ptr(F, mt.in_idx) + mt.src_off; const float* gain = mt.gain_idx >= 0 ? in_ptr(F, mt.gain_idx) + mt.gain_off : nullptr; bf16* dst = (bf16*)((unsigned char*)in_ptr(F, T_WS) + mt.dst_off);
;         while (it < base + cnt) {
	ds_read2_b32 v[0:1], v180 offset0:0 offset1:33
	ds_read2_b32 v[2:3], v180 offset0:66 offset1:99
	ds_read2_b32 v[4:5], v180 offset0:132 offset1:165
	ds_read2_b32 v[6:7], v180 offset0:198 offset1:231
	ds_read2_b32 v[8:9], v180 offset0:8 offset1:41
	ds_read2_b32 v[10:11], v180 offset0:74 offset1:107
	ds_read2_b32 v[12:13], v180 offset0:140 offset1:173
	ds_read2_b32 v[14:15], v180 offset0:206 offset1:239
	s_waitcnt lgkmcnt(4)
	v_cvt_pk_bf16_f32 v186, v0, v1
	v_cvt_pk_bf16_f32 v187, v2, v3
	v_cvt_pk_bf16_f32 v188, v4, v5
	v_cvt_pk_bf16_f32 v189, v6, v7
	global_store_dwordx4 v168, v[186:189], s[42:43] nt
	ds_read2_b32 v[0:1], v180 offset0:16 offset1:49
	ds_read2_b32 v[2:3], v180 offset0:82 offset1:115
	ds_read2_b32 v[4:5], v180 offset0:148 offset1:181
	ds_read2_b32 v[6:7], v180 offset0:214 offset1:247
	s_waitcnt lgkmcnt(4)
	v_cvt_pk_bf16_f32 v190, v8, v9
	v_cvt_pk_bf16_f32 v191, v10, v11
	v_cvt_pk_bf16_f32 v192, v12, v13
	v_cvt_pk_bf16_f32 v193, v14, v15
	global_store_dwordx4 v169, v[190:193], s[42:43] nt
	ds_read2_b32 v[8:9], v180 offset0:24 offset1:57
	ds_read2_b32 v[10:11], v180 offset0:90 offset1:123
	ds_read2_b32 v[12:13], v180 offset0:156 offset1:189
	ds_read2_b32 v[14:15], v180 offset0:222 offset1:255
	s_waitcnt lgkmcnt(4)
	v_cvt_pk_bf16_f32 v186, v0, v1
	v_cvt_pk_bf16_f32 v187, v2, v3
	v_cvt_pk_bf16_f32 v188, v4, v5
	v_cvt_pk_bf16_f32 v189, v6, v7
	global_store_dwordx4 v170, v[186:189], s[42:43] nt
	s_waitcnt lgkmcnt(0)
	v_cvt_pk_bf16_f32 v190, v8, v9
	v_cvt_pk_bf16_f32 v191, v10, v11
	v_cvt_pk_bf16_f32 v192, v12, v13
	v_cvt_pk_bf16_f32 v193, v14, v15
	global_store_dwordx4 v171, v[190:193], s[42:43] nt
	ds_write2_b32 v172, v48, v49 offset1:1
	ds_write2_b32 v172, v50, v51 offset0:2 offset1:3
	ds_write2_b32 v173, v52, v53 offset1:1
	ds_write2_b32 v173, v54, v55 offset0:2 offset1:3
	ds_write2_b32 v174, v56, v57 offset1:1
	ds_write2_b32 v174, v58, v59 offset0:2 offset1:3
	ds_write2_b32 v175, v60, v61 offset1:1
	ds_write2_b32 v175, v62, v63 offset0:2 offset1:3
	ds_write2_b32 v176, v64, v65 offset1:1
	ds_write2_b32 v176, v66, v67 offset0:2 offset1:3
	ds_write2_b32 v177, v68, v69 offset1:1
	ds_write2_b32 v177, v70, v71 offset0:2 offset1:3
	ds_write2_b32 v178, v72, v73 offset1:1
	ds_write2_b32 v178, v74, v75 offset0:2 offset1:3
	ds_write2_b32 v179, v76, v77 offset1:1
	ds_write2_b32 v179, v78, v79 offset0:2 offset1:3
	s_waitcnt lgkmcnt(0)
	ds_read2_b32 v[0:1], v180 offset0:0 offset1:33
	ds_read2_b32 v[2:3], v180 offset0:66 offset1:99
	ds_read2_b32 v[4:5], v180 offset0:132 offset1:165
	ds_read2_b32 v[6:7], v180 offset0:198 offset1:231
	ds_read2_b32 v[8:9], v180 offset0:8 offset1:41
	ds_read2_b32 v[10:11], v180 offset0:74 offset1:107
	ds_read2_b32 v[12:13], v180 offset0:140 offset1:173
	ds_read2_b32 v[14:15], v180 offset0:206 offset1:239
	s_waitcnt lgkmcnt(4)
	v_cvt_pk_bf16_f32 v186, v0, v1
	v_cvt_pk_bf16_f32 v187, v2, v3
	v_cvt_pk_bf16_f32 v188, v4, v5
	v_cvt_pk_bf16_f32 v189, v6, v7
	global_store_dwordx4 v168, v[186:189], s[44:45] nt
	ds_read2_b32 v[0:1], v180 offset0:16 offset1:49
	ds_read2_b32 v[2:3], v180 offset0:82 offset1:115
	ds_read2_b32 v[4:5], v180 offset0:148 offset1:181
	ds_read2_b32 v[6:7], v180 offset0:214 offset1:247
	s_waitcnt lgkmcnt(4)
	v_cvt_pk_bf16_f32 v190, v8, v9
	v_cvt_pk_bf16_f32 v191, v10, v11
	v_cvt_pk_bf16_f32 v192, v12, v13
	v_cvt_pk_bf16_f32 v193, v14, v15
	global_store_dwordx4 v169, v[190:193], s[44:45] nt
	ds_read2_b32 v[8:9], v180 offset0:24 offset1:57
	ds_read2_b32 v[10:11], v180 offset0:90 offset1:123
	ds_read2_b32 v[12:13], v180 offset0:156 offset1:189
	ds_read2_b32 v[14:15], v180 offset0:222 offset1:255
	s_waitcnt lgkmcnt(4)
	v_cvt_pk_bf16_f32 v186, v0, v1
	v_cvt_pk_bf16_f32 v187, v2, v3
	v_cvt_pk_bf16_f32 v188, v4, v5
	v_cvt_pk_bf16_f32 v189, v6, v7
	global_store_dwordx4 v170, v[186:189], s[44:45] nt
	s_waitcnt lgkmcnt(0)
	v_cvt_pk_bf16_f32 v190, v8, v9
	v_cvt_pk_bf16_f32 v191, v10, v11
	v_cvt_pk_bf16_f32 v192, v12, v13
	v_cvt_pk_bf16_f32 v193, v14, v15
	global_store_dwordx4 v171, v[190:193], s[44:45] nt
	s_add_u32 s20, s20, s21
.Lcvb_m24_done:
	s_mov_b32 s22, s23
	s_add_u32 s23, s22, 0x400
	s_cmp_ge_u32 s20, s23
	s_cbranch_scc1 .Lcvb_m28_done
	s_add_i32 s4, 0, 0x20420
	v_mov_b32_e32 v0, s4
	ds_read_b64 v[2:3], v0
	s_waitcnt lgkmcnt(0)
	s_nop 0
	v_readfirstlane_b32 s24, v2
	v_readfirstlane_b32 s25, v3
	s_add_u32 s24, s24, 0x1000000
	s_addc_u32 s25, s25, 0
	s_add_u32 s28, s58, 0x9900000
	s_addc_u32 s29, s59, 0
	s_mov_b32 s30, 0x2000
	s_mov_b32 s31, 0x1000
	s_mov_b32 s34, 0x8000000
	s_mov_b32 s35, 32
	s_mov_b32 s36, 0
	v_mul_lo_u32 v0, v183, s30
	v_lshl_add_u32 v160, v184, 4, v0
	v_add_u32_e32 v161, 0x10000, v160
	v_add_u32_e32 v162, 0x20000, v160
	v_add_u32_e32 v163, 0x30000, v160
	v_add_u32_e32 v164, 0x40000, v160
	v_add_u32_e32 v165, 0x50000, v160
	v_add_u32_e32 v166, 0x60000, v160
	v_add_u32_e32 v167, 0x70000, v160
	v_mul_lo_u32 v0, v183, s31
	v_lshl_add_u32 v168, v184, 4, v0
	v_add_u32_e32 v169, 0x8000, v168
	v_add_u32_e32 v170, 0x10000, v168
	v_add_u32_e32 v171, 0x18000, v168

; #define GAS __attribute__((address_space(1)))
; #define LAS __attribute__((address_space(3)))
; #define LDS_WAIT() asm volatile("s_waitcnt lgkmcnt(0)" ::: "memory")
; __device__ __forceinline__ unsigned pk2(float lo, float hi) { unsigned r; asm("v_cvt_pk_bf16_f32 %0, %1, %2" : "=v"(r) : "v"(lo), "v"(hi)); return r; }
; __device__ __forceinline__ void conv_load(const float* W, int K, int N, int Np, int item, int lane, f32x4 (&v)[2][8]) {
;     const int nblk = Np / 64, kb = item / nblk, nb = item % nblk, k0 = 64 * kb, n0 = 64 * nb;
;     const int kr = lane >> 3, n4 = lane & 7;
; #pragma unroll
;     for (int hf = 0; hf < 2; ++hf)
; #pragma unroll
;         for (int i = 0; i < 8; ++i) { const int k = k0 + 8 * i + kr, n = n0 + 32 * hf + 4 * n4;
;             v[hf][i] = (k < K && n < N) ? __builtin_nontemporal_load((const GAS f32x4*)(W + (size_t)k * N + n)) : (f32x4){0.f, 0.f, 0.f, 0.f}; }
; }
; __device__ __forceinline__ void conv_proc(f32x4 (&v)[2][8], const float* gain, int K, int Kp, int Np, int ilv, bf16* WT, LAS float* scr, int item, int lane) {
;     const int nblk = Np / 64, kb = item / nblk, nb = item % nblk, k0 = 64 * kb, n0 = 64 * nb;
;     const int d0 = ilv ? (((n0 % ilv) >> 7) * 256 + (n0 / ilv) * 128 + ((n0 % ilv) & 127)) : n0;
;     const int kr = lane >> 3, n4 = lane & 7;
;     if (gain) {
; #pragma unroll
;         for (int i = 0; i < 8; ++i) { const int k = k0 + 8 * i + kr; const float g = k < K ? gain[k] : 0.f; v[0][i] *= g; v[1][i] *= g; } }
;     const int c = lane & 7;
; #pragma unroll
;     for (int hf = 0; hf < 2; ++hf) {
; #pragma unroll
;         for (int i = 0; i < 8; ++i) { LAS float* d = scr + (8 * i + kr) * 33 + 4 * n4; d[0] = v[hf][i][0]; d[1] = v[hf][i][1]; d[2] = v[hf][i][2]; d[3] = v[hf][i][3]; }
;         LDS_WAIT(); asm volatile("" ::: "memory");
; #pragma unroll
;         for (int j = 0; j < 4; ++j) { const int nn = (lane >> 3) + 8 * j; const LAS float* sp = scr + (8 * c) * 33 + nn;
;             v4u o; o.x = pk2(sp[0 * 33], sp[1 * 33]); o.y = pk2(sp[2 * 33], sp[3 * 33]); o.z = pk2(sp[4 * 33], sp[5 * 33]); o.w = pk2(sp[6 * 33], sp[7 * 33]);
;             __builtin_nontemporal_store(o, (GAS v4u*)(WT + (size_t)(d0 + 32 * hf + nn) * Kp + k0 + 8 * c)); }
;         LDS_WAIT(); asm volatile("" ::: "memory");
;     }
; }
.Lcvb_noilv3:
	s_mul_i32 s7, s7, s31
	s_lshl_b32 s6, s4, 7
	s_add_u32 s7, s7, s6
	s_add_u32 s50, s28, s7
	s_addc_u32 s51, s29, 0
	s_lshl_b32 s6, s31, 5
	s_add_u32 s54, s50, s6
	s_addc_u32 s55, s51, 0
	global_load_dwordx4 v[16:19], v160, s[38:39] nt
	global_load_dwordx4 v[20:23], v161, s[38:39] nt
	global_load_dwordx4 v[24:27], v162, s[38:39] nt
	global_load_dwordx4 v[28:31], v163, s[38:39] nt
	global_load_dwordx4 v[32:35], v164, s[38:39] nt
	global_load_dwordx4 v[36:39], v165, s[38:39] nt
	global_load_dwordx4 v[40:43], v166, s[38:39] nt
	global_load_dwordx4 v[44:47], v167, s[38:39] nt
	global_load_dwordx4 v[48:51], v160, s[38:39] offset:128 nt
	global_load_dwordx4 v[52:55], v161, s[38:39] offset:128 nt
	global_load_dwordx4 v[56:59], v162, s[38:39] offset:128 nt
	global_load_dwordx4 v[60:63], v163, s[38:39] offset:128 nt
	global_load_dwordx4 v[64:67], v164, s[38:39] offset:128 nt
	global_load_dwordx4 v[68:71], v165, s[38:39] offset:128 nt
	global_load_dwordx4 v[72:75], v166, s[38:39] offset:128 nt
	global_load_dwordx4 v[76:79], v167, s[38:39] offset:128 nt
	global_load_dwordx4 v[80:83], v160, s[46:47] nt
	global_load_dwordx4 v[84:87], v161, s[46:47] nt
	global_load_dwordx4 v[88:91], v162, s[46:47] nt
	global_load_dwordx4 v[92:95], v163, s[46:47] nt
	global_load_dwordx4 v[96:99], v164, s[46:47] nt
	global_load_dwordx4 v[100:103], v165, s[46:47] nt
	global_load_dwordx4 v[104:107], v166, s[46:47] nt
	global_load_dwordx4 v[108:111], v167, s[46:47] nt
	global_load_dwordx4 v[112:115], v160, s[46:47] offset:128 nt
	global_load_dwordx4 v[116:119], v161, s[46:47] offset:128 nt
	global_load_dwordx4 v[120:123], v162, s[46:47] offset:128 nt
	global_load_dwordx4 v[124:127], v163, s[46:47] offset:128 nt
	global_load_dwordx4 v[128:131], v164, s[46:47] offset:128 nt
	global_load_dwordx4 v[132:135], v165, s[46:47] offset:128 nt
	global_load_dwordx4 v[136:139], v166, s[46:47] offset:128 nt
	global_load_dwordx4 v[140:143], v167, s[46:47] offset:128 nt
	s_waitcnt vmcnt(16)
	ds_write2_b32 v172, v16, v17 offset1:1
	ds_write2_b32 v172, v18, v19 offset0:2 offset1:3
	ds_write2_b32 v173, v20, v21 offset1:1
	ds_write2_b32 v173, v22, v23 offset0:2 offset1:3
	ds_write2_b32 v174, v24, v25 offset1:1
	ds_write2_b32 v174, v26, v27 offset0:2 offset1:3
	ds_write2_b32 v175, v28, v29 offset1:1
	ds_write2_b32 v175, v30, v31 offset0:2 offset1:3
	ds_write2_b32 v176, v32, v33 offset1:1
	ds_write2_b32 v176, v34, v35 offset0:2 offset1:3
	ds_write2_b32 v177, v36, v37 offset1:1
	ds_write2_b32 v177, v38, v39 offset0:2 offset1:3
	ds_write2_b32 v178, v40, v41 offset1:1
	ds_write2_b32 v178, v42, v43 offset0:2 offset1:3
	ds_write2_b32 v179, v44, v45 offset1:1
	ds_write2_b32 v179, v46, v47 offset0:2 offset1:3
	s_waitcnt lgkmcnt(0)
	ds_read2_b32 v[0:1], v180 offset0:0 offset1:33
	ds_read2_b32 v[2:3], v180 offset0:66 offset1:99
	ds_read2_b32 v[4:5], v180 offset0:132 offset1:165
	ds_read2_b32 v[6:7], v180 offset0:198 offset1:231
	ds_read2_b32 v[8:9], v180 offset0:8 offset1:41
	ds_read2_b32 v[10:11], v180 offset0:74 offset1:107
	ds_read2_b32 v[12:13], v180 offset0:140 offset1:173
	ds_read2_b32 v[14:15], v180 offset0:206 offset1:239
	s_waitcnt lgkmcnt(4)
	v_cvt_pk_bf16_f32 v186, v0, v1
	v_cvt_pk_bf16_f32 v187, v2, v3
	v_cvt_pk_bf16_f32 v188, v4, v5
	v_cvt_pk_bf16_f32 v189, v6, v7
	global_store_dwordx4 v168, v[186:189], s[42:43] nt
	ds_read2_b32 v[0:1], v180 offset0:16 offset1:49
	ds_read2_b32 v[2:3], v180 offset0:82 offset1:115
	ds_read2_b32 v[4:5], v180 offset0:148 offset1:181
	ds_read2_b32 v[6:7], v180 offset0:214 offset1:247
	s_waitcnt lgkmcnt(4)
	v_cvt_pk_bf16_f32 v190, v8, v9
	v_cvt_pk_bf16_f32 v191, v10, v11
	v_cvt_pk_bf16_f32 v192, v12, v13
	v_cvt_pk_bf16_f32 v193, v14, v15
	global_store_dwordx4 v169, v[190:193], s[42:43] nt
	ds_read2_b32 v[8:9], v180 offset0:24 offset1:57
	ds_read2_b32 v[10:11], v180 offset0:90 offset1:123
	ds_read2_b32 v[12:13], v180 offset0:156 offset1:189
	ds_read2_b32 v[14:15], v180 offset0:222 offset1:255
	s_waitcnt lgkmcnt(4)
	v_cvt_pk_bf16_f32 v186, v0, v1
	v_cvt_pk_bf16_f32 v187, v2, v3
	v_cvt_pk_bf16_f32 v188, v4, v5
	v_cvt_pk_bf16_f32 v189, v6, v7
	global_store_dwordx4 v170, v[186:189], s[42:43] nt
	s_waitcnt lgkmcnt(0)
	v_cvt_pk_bf16_f32 v190, v8, v9
	v_cvt_pk_bf16_f32 v191, v10, v11
	v_cvt_pk_bf16_f32 v192, v12, v13
	v_cvt_pk_bf16_f32 v193, v14, v15
	global_store_dwordx4 v171, v[190:193], s[42:43] nt
	ds_write2_b32 v172, v48, v49 offset1:1
	ds_write2_b32 v172, v50, v51 offset0:2 offset1:3
	ds_write2_b32 v173, v52, v53 offset1:1
	ds_write2_b32 v173, v54, v55 offset0:2 offset1:3
	ds_write2_b32 v174, v56, v57 offset1:1
	ds_write2_b32 v174, v58, v59 offset0:2 offset1:3
	ds_write2_b32 v175, v60, v61 offset1:1
	ds_write2_b32 v175, v62, v63 offset0:2 offset1:3
	ds_write2_b32 v176, v64, v65 offset1:1
	ds_write2_b32 v176, v66, v67 offset0:2 offset1:3
	ds_write2_b32 v177, v68, v69 offset1:1
	ds_write2_b32 v177, v70, v71 offset0:2 offset1:3
	ds_write2_b32 v178, v72, v73 offset1:1
	ds_write2_b32 v178, v74, v75 offset0:2 offset1:3
	ds_write2_b32 v179, v76, v77 offset1:1
	ds_write2_b32 v179, v78, v79 offset0:2 offset1:3
	s_waitcnt lgkmcnt(0)
	ds_read2_b32 v[0:1], v180 offset0:0 offset1:33
	ds_read2_b32 v[2:3], v180 offset0:66 offset1:99
	ds_read2_b32 v[4:5], v180 offset0:132 offset1:165
	ds_read2_b32 v[6:7], v180 offset0:198 offset1:231
	ds_read2_b32 v[8:9], v180 offset0:8 offset1:41
	ds_read2_b32 v[10:11], v180 offset0:74 offset1:107
	ds_read2_b32 v[12:13], v180 offset0:140 offset1:173
	ds_read2_b32 v[14:15], v180 offset0:206 offset1:239
	s_waitcnt lgkmcnt(4)
; #define GAS __attribute__((address_space(1)))
; #define LAS __attribute__((address_space(3)))
; #define LDS_WAIT() asm volatile("s_waitcnt lgkmcnt(0)" ::: "memory")
; __device__ __forceinline__ unsigned pk2(float lo, float hi) { unsigned r; asm("v_cvt_pk_bf16_f32 %0, %1, %2" : "=v"(r) : "v"(lo), "v"(hi)); return r; }
; __device__ __forceinline__ void conv_proc(f32x4 (&v)[2][8], const float* gain, int K, int Kp, int Np, int ilv, bf16* WT, LAS float* scr, int item, int lane) {
;     const int nblk = Np / 64, kb = item / nblk, nb = item % nblk, k0 = 64 * kb, n0 = 64 * nb;
;     const int d0 = ilv ? (((n0 % ilv) >> 7) * 256 + (n0 / ilv) * 128 + ((n0 % ilv) & 127)) : n0;
;     const int kr = lane >> 3, n4 = lane & 7;
;     if (gain) {
; #pragma unroll
;         for (int i = 0; i < 8; ++i) { const int k = k0 + 8 * i + kr; const float g = k < K ? gain[k] : 0.f; v[0][i] *= g; v[1][i] *= g; } }
;     const int c = lane & 7;
; #pragma unroll
;     for (int hf = 0; hf < 2; ++hf) {
; #pragma unroll
;         for (int i = 0; i < 8; ++i) { LAS float* d = scr + (8 * i + kr) * 33 + 4 * n4; d[0] = v[hf][i][0]; d[1] = v[hf][i][1]; d[2] = v[hf][i][2]; d[3] = v[hf][i][3]; }
;         LDS_WAIT(); asm volatile("" ::: "memory");
; #pragma unroll
;         for (int j = 0; j < 4; ++j) { const int nn = (lane >> 3) + 8 * j; const LAS float* sp = scr + (8 * c) * 33 + nn;
;             v4u o; o.x = pk2(sp[0 * 33], sp[1 * 33]); o.y = pk2(sp[2 * 33], sp[3 * 33]); o.z = pk2(sp[4 * 33], sp[5 * 33]); o.w = pk2(sp[6 * 33], sp[7 * 33]);
;             __builtin_nontemporal_store(o, (GAS v4u*)(WT + (size_t)(d0 + 32 * hf + nn) * Kp + k0 + 8 * c)); }
;         LDS_WAIT(); asm volatile("" ::: "memory");
;     }
; }
	v_cvt_pk_bf16_f32 v186, v0, v1
	v_cvt_pk_bf16_f32 v187, v2, v3
	v_cvt_pk_bf16_f32 v188, v4, v5
	v_cvt_pk_bf16_f32 v189, v6, v7
	global_store_dwordx4 v168, v[186:189], s[44:45] nt
	ds_read2_b32 v[0:1], v180 offset0:16 offset1:49
	ds_read2_b32 v[2:3], v180 offset0:82 offset1:115
	ds_read2_b32 v[4:5], v180 offset0:148 offset1:181
	ds_read2_b32 v[6:7], v180 offset0:214 offset1:247
	s_waitcnt lgkmcnt(4)
	v_cvt_pk_bf16_f32 v190, v8, v9
	v_cvt_pk_bf16_f32 v191, v10, v11
	v_cvt_pk_bf16_f32 v192, v12, v13
	v_cvt_pk_bf16_f32 v193, v14, v15
	global_store_dwordx4 v169, v[190:193], s[44:45] nt
	ds_read2_b32 v[8:9], v180 offset0:24 offset1:57
	ds_read2_b32 v[10:11], v180 offset0:90 offset1:123
	ds_read2_b32 v[12:13], v180 offset0:156 offset1:189
	ds_read2_b32 v[14:15], v180 offset0:222 offset1:255
	s_waitcnt lgkmcnt(4)
	v_cvt_pk_bf16_f32 v186, v0, v1
	v_cvt_pk_bf16_f32 v187, v2, v3
	v_cvt_pk_bf16_f32 v188, v4, v5
	v_cvt_pk_bf16_f32 v189, v6, v7
	global_store_dwordx4 v170, v[186:189], s[44:45] nt
	s_waitcnt lgkmcnt(0)
	v_cvt_pk_bf16_f32 v190, v8, v9
	v_cvt_pk_bf16_f32 v191, v10, v11
	v_cvt_pk_bf16_f32 v192, v12, v13
	v_cvt_pk_bf16_f32 v193, v14, v15
	global_store_dwordx4 v171, v[190:193], s[44:45] nt
	s_waitcnt vmcnt(8)
	ds_write2_b32 v172, v80, v81 offset1:1
	ds_write2_b32 v172, v82, v83 offset0:2 offset1:3
	ds_write2_b32 v173, v84, v85 offset1:1
	ds_write2_b32 v173, v86, v87 offset0:2 offset1:3
	ds_write2_b32 v174, v88, v89 offset1:1
	ds_write2_b32 v174, v90, v91 offset0:2 offset1:3
	ds_write2_b32 v175, v92, v93 offset1:1
	ds_write2_b32 v175, v94, v95 offset0:2 offset1:3
	ds_write2_b32 v176, v96, v97 offset1:1
	ds_write2_b32 v176, v98, v99 offset0:2 offset1:3
	ds_write2_b32 v177, v100, v101 offset1:1
	ds_write2_b32 v177, v102, v103 offset0:2 offset1:3
	ds_write2_b32 v178, v104, v105 offset1:1
	ds_write2_b32 v178, v106, v107 offset0:2 offset1:3
	ds_write2_b32 v179, v108, v109 offset1:1
	ds_write2_b32 v179, v110, v111 offset0:2 offset1:3
	s_waitcnt lgkmcnt(0)
	ds_read2_b32 v[0:1], v180 offset0:0 offset1:33
	ds_read2_b32 v[2:3], v180 offset0:66 offset1:99
	ds_read2_b32 v[4:5], v180 offset0:132 offset1:165
	ds_read2_b32 v[6:7], v180 offset0:198 offset1:231
	ds_read2_b32 v[8:9], v180 offset0:8 offset1:41
	ds_read2_b32 v[10:11], v180 offset0:74 offset1:107
	ds_read2_b32 v[12:13], v180 offset0:140 offset1:173
	ds_read2_b32 v[14:15], v180 offset0:206 offset1:239
	s_waitcnt lgkmcnt(4)
	v_cvt_pk_bf16_f32 v186, v0, v1
	v_cvt_pk_bf16_f32 v187, v2, v3
	v_cvt_pk_bf16_f32 v188, v4, v5
	v_cvt_pk_bf16_f32 v189, v6, v7
	global_store_dwordx4 v168, v[186:189], s[50:51] nt
	ds_read2_b32 v[0:1], v180 offset0:16 offset1:49
	ds_read2_b32 v[2:3], v180 offset0:82 offset1:115
	ds_read2_b32 v[4:5], v180 offset0:148 offset1:181
	ds_read2_b32 v[6:7], v180 offset0:214 offset1:247
	s_waitcnt lgkmcnt(4)
	v_cvt_pk_bf16_f32 v190, v8, v9
	v_cvt_pk_bf16_f32 v191, v10, v11
	v_cvt_pk_bf16_f32 v192, v12, v13
	v_cvt_pk_bf16_f32 v193, v14, v15
	global_store_dwordx4 v169, v[190:193], s[50:51] nt
	ds_read2_b32 v[8:9], v180 offset0:24 offset1:57
	ds_read2_b32 v[10:11], v180 offset0:90 offset1:123
	ds_read2_b32 v[12:13], v180 offset0:156 offset1:189
	ds_read2_b32 v[14:15], v180 offset0:222 offset1:255
	s_waitcnt lgkmcnt(4)
	v_cvt_pk_bf16_f32 v186, v0, v1
	v_cvt_pk_bf16_f32 v187, v2, v3
	v_cvt_pk_bf16_f32 v188, v4, v5
	v_cvt_pk_bf16_f32 v189, v6, v7
	global_store_dwordx4 v170, v[186:189], s[50:51] nt
	s_waitcnt lgkmcnt(0)
	v_cvt_pk_bf16_f32 v190, v8, v9
	v_cvt_pk_bf16_f32 v191, v10, v11
	v_cvt_pk_bf16_f32 v192, v12, v13
	v_cvt_pk_bf16_f32 v193, v14, v15
	global_store_dwordx4 v171, v[190:193], s[50:51] nt
	ds_write2_b32 v172, v112, v113 offset1:1
	ds_write2_b32 v172, v114, v115 offset0:2 offset1:3
	ds_write2_b32 v173, v116, v117 offset1:1
	ds_write2_b32 v173, v118, v119 offset0:2 offset1:3
	ds_write2_b32 v174, v120, v121 offset1:1
	ds_write2_b32 v174, v122, v123 offset0:2 offset1:3
	ds_write2_b32 v175, v124, v125 offset1:1
	ds_write2_b32 v175, v126, v127 offset0:2 offset1:3
	ds_write2_b32 v176, v128, v129 offset1:1
	ds_write2_b32 v176, v130, v131 offset0:2 offset1:3
	ds_write2_b32 v177, v132, v133 offset1:1
	ds_write2_b32 v177, v134, v135 offset0:2 offset1:3
	ds_write2_b32 v178, v136, v137 offset1:1
	ds_write2_b32 v178, v138, v139 offset0:2 offset1:3
	ds_write2_b32 v179, v140, v141 offset1:1
	ds_write2_b32 v179, v142, v143 offset0:2 offset1:3
	s_waitcnt lgkmcnt(0)
	ds_read2_b32 v[0:1], v180 offset0:0 offset1:33
	ds_read2_b32 v[2:3], v180 offset0:66 offset1:99
	ds_read2_b32 v[4:5], v180 offset0:132 offset1:165
	ds_read2_b32 v[6:7], v180 offset0:198 offset1:231
	ds_read2_b32 v[8:9], v180 offset0:8 offset1:41
	ds_read2_b32 v[10:11], v180 offset0:74 offset1:107
	ds_read2_b32 v[12:13], v180 offset0:140 offset1:173
	ds_read2_b32 v[14:15], v180 offset0:206 offset1:239
	s_waitcnt lgkmcnt(4)
	v_cvt_pk_bf16_f32 v186, v0, v1
	v_cvt_pk_bf16_f32 v187, v2, v3
	v_cvt_pk_bf16_f32 v188, v4, v5
	v_cvt_pk_bf16_f32 v189, v6, v7
	global_store_dwordx4 v168, v[186:189], s[54:55] nt
	ds_read2_b32 v[0:1], v180 offset0:16 offset1:49
	ds_read2_b32 v[2:3], v180 offset0:82 offset1:115
	ds_read2_b32 v[4:5], v180 offset0:148 offset1:181
	ds_read2_b32 v[6:7], v180 offset0:214 offset1:247
	s_waitcnt lgkmcnt(4)
	v_cvt_pk_bf16_f32 v190, v8, v9
	v_cvt_pk_bf16_f32 v191, v10, v11
	v_cvt_pk_bf16_f32 v192, v12, v13
	v_cvt_pk_bf16_f32 v193, v14, v15
	global_store_dwordx4 v169, v[190:193], s[54:55] nt
	ds_read2_b32 v[8:9], v180 offset0:24 offset1:57
	ds_read2_b32 v[10:11], v180 offset0:90 offset1:123
	ds_read2_b32 v[12:13], v180 offset0:156 offset1:189
	ds_read2_b32 v[14:15], v180 offset0:222 offset1:255
	s_waitcnt lgkmcnt(4)
	v_cvt_pk_bf16_f32 v186, v0, v1
	v_cvt_pk_bf16_f32 v187, v2, v3
	v_cvt_pk_bf16_f32 v188, v4, v5
	v_cvt_pk_bf16_f32 v189, v6, v7
	global_store_dwordx4 v170, v[186:189], s[54:55] nt
	s_waitcnt lgkmcnt(0)
	v_cvt_pk_bf16_f32 v190, v8, v9
	v_cvt_pk_bf16_f32 v191, v10, v11
	v_cvt_pk_bf16_f32 v192, v12, v13
	v_cvt_pk_bf16_f32 v193, v14, v15
	global_store_dwordx4 v171, v[190:193], s[54:55] nt
	s_lshl_b32 s4, s21, 1
	s_add_u32 s20, s20, s4
	s_cmp_lt_u32 s20, s23
	s_cbranch_scc1 .Lcvb_m28_loop
	s_branch .Lcvb_m28_done
; #define GAS __attribute__((address_space(1)))
; #define LAS __attribute__((address_space(3)))
; #define LDS_WAIT() asm volatile("s_waitcnt lgkmcnt(0)" ::: "memory")
; __device__ __forceinline__ unsigned pk2(float lo, float hi) { unsigned r; asm("v_cvt_pk_bf16_f32 %0, %1, %2" : "=v"(r) : "v"(lo), "v"(hi)); return r; }
; __device__ __forceinline__ void conv_proc(f32x4 (&v)[2][8], const float* gain, int K, int Kp, int Np, int ilv, bf16* WT, LAS float* scr, int item, int lane) {
;     const int nblk = Np / 64, kb = item / nblk, nb = item % nblk, k0 = 64 * kb, n0 = 64 * nb;
;     const int d0 = ilv ? (((n0 % ilv) >> 7) * 256 + (n0 / ilv) * 128 + ((n0 % ilv) & 127)) : n0;
;     const int kr = lane >> 3, n4 = lane & 7;
;     if (gain) {
; #pragma unroll
;         for (int i = 0; i < 8; ++i) { const int k = k0 + 8 * i + kr; const float g = k < K ? gain[k] : 0.f; v[0][i] *= g; v[1][i] *= g; } }
;     const int c = lane & 7;
; #pragma unroll
;     for (int hf = 0; hf < 2; ++hf) {
; #pragma unroll
;         for (int i = 0; i < 8; ++i) { LAS float* d = scr + (8 * i + kr) * 33 + 4 * n4; d[0] = v[hf][i][0]; d[1] = v[hf][i][1]; d[2] = v[hf][i][2]; d[3] = v[hf][i][3]; }
;         LDS_WAIT(); asm volatile("" ::: "memory");
; #pragma unroll
;         for (int j = 0; j < 4; ++j) { const int nn = (lane >> 3) + 8 * j; const LAS float* sp = scr + (8 * c) * 33 + nn;
;             v4u o; o.x = pk2(sp[0 * 33], sp[1 * 33]); o.y = pk2(sp[2 * 33], sp[3 * 33]); o.z = pk2(sp[4 * 33], sp[5 * 33]); o.w = pk2(sp[6 * 33], sp[7 * 33]);
;             __builtin_nontemporal_store(o, (GAS v4u*)(WT + (size_t)(d0 + 32 * hf + nn) * Kp + k0 + 8 * c)); }
;         LDS_WAIT(); asm volatile("" ::: "memory");
;     }
; }
.Lcvb_m28_oneitem:
	global_load_dwordx4 v[16:19], v160, s[38:39] nt
	global_load_dwordx4 v[20:23], v161, s[38:39] nt
	global_load_dwordx4 v[24:27], v162, s[38:39] nt
	global_load_dwordx4 v[28:31], v163, s[38:39] nt
	global_load_dwordx4 v[32:35], v164, s[38:39] nt
	global_load_dwordx4 v[36:39], v165, s[38:39] nt
	global_load_dwordx4 v[40:43], v166, s[38:39] nt
	global_load_dwordx4 v[44:47], v167, s[38:39] nt
	global_load_dwordx4 v[48:51], v160, s[38:39] offset:128 nt
	global_load_dwordx4 v[52:55], v161, s[38:39] offset:128 nt
	global_load_dwordx4 v[56:59], v162, s[38:39] offset:128 nt
	global_load_dwordx4 v[60:63], v163, s[38:39] offset:128 nt
	global_load_dwordx4 v[64:67], v164, s[38:39] offset:128 nt
	global_load_dwordx4 v[68:71], v165, s[38:39] offset:128 nt
	global_load_dwordx4 v[72:75], v166, s[38:39] offset:128 nt
	global_load_dwordx4 v[76:79], v167, s[38:39] offset:128 nt
	s_waitcnt vmcnt(0)
	ds_write2_b32 v172, v16, v17 offset1:1
	ds_write2_b32 v172, v18, v19 offset0:2 offset1:3
	ds_write2_b32 v173, v20, v21 offset1:1
	ds_write2_b32 v173, v22, v23 offset0:2 offset1:3
	ds_write2_b32 v174, v24, v25 offset1:1
	ds_write2_b32 v174, v26, v27 offset0:2 offset1:3
	ds_write2_b32 v175, v28, v29 offset1:1
	ds_write2_b32 v175, v30, v31 offset0:2 offset1:3
	ds_write2_b32 v176, v32, v33 offset1:1
	ds_write2_b32 v176, v34, v35 offset0:2 offset1:3
	ds_write2_b32 v177, v36, v37 offset1:1
	ds_write2_b32 v177, v38, v39 offset0:2 offset1:3
	ds_write2_b32 v178, v40, v41 offset1:1
	ds_write2_b32 v178, v42, v43 offset0:2 offset1:3
	ds_write2_b32 v179, v44, v45 offset1:1
	ds_write2_b32 v179, v46, v47 offset0:2 offset1:3
	s_waitcnt lgkmcnt(0)
	ds_read2_b32 v[0:1], v180 offset0:0 offset1:33
	ds_read2_b32 v[2:3], v180 offset0:66 offset1:99
	ds_read2_b32 v[4:5], v180 offset0:132 offset1:165
	ds_read2_b32 v[6:7], v180 offset0:198 offset1:231
	ds_read2_b32 v[8:9], v180 offset0:8 offset1:41
	ds_read2_b32 v[10:11], v180 offset0:74 offset1:107
	ds_read2_b32 v[12:13], v180 offset0:140 offset1:173
	ds_read2_b32 v[14:15], v180 offset0:206 offset1:239
	s_waitcnt lgkmcnt(4)
	v_cvt_pk_bf16_f32 v186, v0, v1
	v_cvt_pk_bf16_f32 v187, v2, v3
	v_cvt_pk_bf16_f32 v188, v4, v5
	v_cvt_pk_bf16_f32 v189, v6, v7
	global_store_dwordx4 v168, v[186:189], s[42:43] nt
	ds_read2_b32 v[0:1], v180 offset0:16 offset1:49
	ds_read2_b32 v[2:3], v180 offset0:82 offset1:115
	ds_read2_b32 v[4:5], v180 offset0:148 offset1:181
	ds_read2_b32 v[6:7], v180 offset0:214 offset1:247
	s_waitcnt lgkmcnt(4)
	v_cvt_pk_bf16_f32 v190, v8, v9
	v_cvt_pk_bf16_f32 v191, v10, v11
	v_cvt_pk_bf16_f32 v192, v12, v13
	v_cvt_pk_bf16_f32 v193, v14, v15
	global_store_dwordx4 v169, v[190:193], s[42:43] nt
	ds_read2_b32 v[8:9], v180 offset0:24 offset1:57
	ds_read2_b32 v[10:11], v180 offset0:90 offset1:123
	ds_read2_b32 v[12:13], v180 offset0:156 offset1:189
	ds_read2_b32 v[14:15], v180 offset0:222 offset1:255
	s_waitcnt lgkmcnt(4)
	v_cvt_pk_bf16_f32 v186, v0, v1
	v_cvt_pk_bf16_f32 v187, v2, v3
	v_cvt_pk_bf16_f32 v188, v4, v5
	v_cvt_pk_bf16_f32 v189, v6, v7
	global_store_dwordx4 v170, v[186:189], s[42:43] nt
	s_waitcnt lgkmcnt(0)
	v_cvt_pk_bf16_f32 v190, v8, v9
	v_cvt_pk_bf16_f32 v191, v10, v11
	v_cvt_pk_bf16_f32 v192, v12, v13
	v_cvt_pk_bf16_f32 v193, v14, v15
	global_store_dwordx4 v171, v[190:193], s[42:43] nt
	ds_write2_b32 v172, v48, v49 offset1:1
	ds_write2_b32 v172, v50, v51 offset0:2 offset1:3
	ds_write2_b32 v173, v52, v53 offset1:1
	ds_write2_b32 v173, v54, v55 offset0:2 offset1:3
	ds_write2_b32 v174, v56, v57 offset1:1
	ds_write2_b32 v174, v58, v59 offset0:2 offset1:3
	ds_write2_b32 v175, v60, v61 offset1:1
	ds_write2_b32 v175, v62, v63 offset0:2 offset1:3
	ds_write2_b32 v176, v64, v65 offset1:1
	ds_write2_b32 v176, v66, v67 offset0:2 offset1:3
	ds_write2_b32 v177, v68, v69 offset1:1
	ds_write2_b32 v177, v70, v71 offset0:2 offset1:3
	ds_write2_b32 v178, v72, v73 offset1:1
	ds_write2_b32 v178, v74, v75 offset0:2 offset1:3
	ds_write2_b32 v179, v76, v77 offset1:1
	ds_write2_b32 v179, v78, v79 offset0:2 offset1:3
	s_waitcnt lgkmcnt(0)
	ds_read2_b32 v[0:1], v180 offset0:0 offset1:33
	ds_read2_b32 v[2:3], v180 offset0:66 offset1:99
	ds_read2_b32 v[4:5], v180 offset0:132 offset1:165
	ds_read2_b32 v[6:7], v180 offset0:198 offset1:231
	ds_read2_b32 v[8:9], v180 offset0:8 offset1:41
	ds_read2_b32 v[10:11], v180 offset0:74 offset1:107
	ds_read2_b32 v[12:13], v180 offset0:140 offset1:173
	ds_read2_b32 v[14:15], v180 offset0:206 offset1:239
	s_waitcnt lgkmcnt(4)
	v_cvt_pk_bf16_f32 v186, v0, v1
	v_cvt_pk_bf16_f32 v187, v2, v3
	v_cvt_pk_bf16_f32 v188, v4, v5
	v_cvt_pk_bf16_f32 v189, v6, v7
	global_store_dwordx4 v168, v[186:189], s[44:45] nt
	ds_read2_b32 v[0:1], v180 offset0:16 offset1:49
	ds_read2_b32 v[2:3], v180 offset0:82 offset1:115
	ds_read2_b32 v[4:5], v180 offset0:148 offset1:181
	ds_read2_b32 v[6:7], v180 offset0:214 offset1:247
	s_waitcnt lgkmcnt(4)
	v_cvt_pk_bf16_f32 v190, v8, v9
	v_cvt_pk_bf16_f32 v191, v10, v11
	v_cvt_pk_bf16_f32 v192, v12, v13
	v_cvt_pk_bf16_f32 v193, v14, v15
	global_store_dwordx4 v169, v[190:193], s[44:45] nt
	ds_read2_b32 v[8:9], v180 offset0:24 offset1:57
	ds_read2_b32 v[10:11], v180 offset0:90 offset1:123
	ds_read2_b32 v[12:13], v180 offset0:156 offset1:189
	ds_read2_b32 v[14:15], v180 offset0:222 offset1:255
	s_waitcnt lgkmcnt(4)
	v_cvt_pk_bf16_f32 v186, v0, v1
	v_cvt_pk_bf16_f32 v187, v2, v3
	v_cvt_pk_bf16_f32 v188, v4, v5
	v_cvt_pk_bf16_f32 v189, v6, v7
	global_store_dwordx4 v170, v[186:189], s[44:45] nt
	s_waitcnt lgkmcnt(0)
	v_cvt_pk_bf16_f32 v190, v8, v9
	v_cvt_pk_bf16_f32 v191, v10, v11
	v_cvt_pk_bf16_f32 v192, v12, v13
	v_cvt_pk_bf16_f32 v193, v14, v15
	global_store_dwordx4 v171, v[190:193], s[44:45] nt
	s_add_u32 s20, s20, s21
.Lcvb_m28_done:
	s_mov_b32 s22, s23
	s_waitcnt vmcnt(0)

; __device__ __forceinline__ void convert_mats(Frame& F, int m_lo, int m_hi, int gw, int NGW) {
;     ...
;     for (int mi = m_lo; mi < m_hi; ++mi) {
;         const MatI mt = kMats[mi]; const int cnt = (mt.Kp / 64) * (mt.Np / 64);
;         const float* src = in_ptr(F, mt.in_idx) + mt.src_off; const float* gain = mt.gain_idx >= 0 ? in_ptr(F, mt.gain_idx) + mt.gain_off : nullptr; bf16* dst = (bf16*)((unsigned char*)in_ptr(F, T_WS) + mt.dst_off);
.Lcsa_m4:
	s_cmp_lg_u32 s67, 4
	s_cbranch_scc1 .Lcsa_m5
	s_mov_b32 s82, 288
	s_mov_b32 s83, 0xe38e39
	s_mov_b32 s84, 0x12000
	s_mov_b32 s85, 0x1000
	s_mov_b32 s86, 0
	s_mov_b32 s87, 9216
	s_mov_b32 s88, 0x9000000
	s_mov_b32 s90, 0x4900000
	s_mov_b32 s93, 0x20418
	s_mov_b32 s89, 0x2000
	s_mov_b32 s94, 0x20410
	s_branch .Lcsa_have
.Lcsa_m5:
	s_cmp_lg_u32 s67, 5
	s_cbranch_scc1 .Lcsa_m6
	s_mov_b32 s82, 96
	s_mov_b32 s83, 0x2aaaaab
	s_mov_b32 s84, 0x6000
	s_mov_b32 s85, 0x1000
	s_mov_b32 s86, 0
	s_mov_b32 s87, 3072
	s_mov_b32 s88, 0x0
	s_mov_b32 s90, 0xc700000
	s_mov_b32 s93, 0x204b8
	s_mov_b32 s89, 0x0
	s_mov_b32 s94, 0x204b0
	s_branch .Lcsa_have
.Lcsa_m6:
	s_mov_b32 s82, 32
	s_mov_b32 s83, 0x8000000
	s_mov_b32 s84, 0x2000
	s_mov_b32 s85, 0x1000
	s_mov_b32 s86, 0
	s_mov_b32 s87, 1024
	s_mov_b32 s88, 0x0
	s_mov_b32 s90, 0xdf00000
	s_mov_b32 s93, 0x204c8
	s_mov_b32 s94, 0

; __device__ __forceinline__ void convert_mats(Frame& F, int m_lo, int m_hi, int gw, int NGW) {
;     LAS float* scr = (LAS float*)(F.lds + F.wave * 16384);
;     int it = gw, base = 0;
;     for (int mi = m_lo; mi < m_hi; ++mi) {
;         const MatI mt = kMats[mi]; const int cnt = (mt.Kp / 64) * (mt.Np / 64);
;         const float* src = in_ptr(F, mt.in_idx) + mt.src_off; const float* gain = mt.gain_idx >= 0 ? in_ptr(F, mt.gain_idx) + mt.gain_off : nullptr; bf16* dst = (bf16*)((unsigned char*)in_ptr(F, T_WS) + mt.dst_off);
;         while (it < base + cnt) {
; template <int L> __device__ __forceinline__ void layer_phases(Frame& F, const int lo, const int hi, const XcdBarrier& bar, const int bid) {
;     ...
;         {
;             const int rem = (M / 256) * (2 * FF / 256) % F.G, nidle = rem ? F.G - rem : 0, ci = bid - rem;
;             if (nidle > 0 && ci >= 0) {
;                 if constexpr (L == 0) {
;                     pg8::Gemm g2{(const bf16*)(ws + WS_PB), (const bf16*)(ws + WS_WPP), M, 4 * D, PLE, (size_t)M * PLE * 2, 8, 1 << 30};
;                     pg8::StaticOrder S2; S2.init(M, 4 * D, nidle, ci);
;                     pg8::EpiScaleBf16<false> E2{(bf16*)(ws + WS_PPO), D, nullptr, D, (size_t)M * D, nullptr};
;                     pg8::gemm_phase<pg8::EpiScaleBf16<false>, pg8::StaticOrder, false, true>(F.lds, g2, S2, E2, F.wave);
;                 } else if constexpr (L == 1) { F.ids(); convert_mats(F, 27, 29, ci * NWAVES + F.wave, nidle * NWAVES); }
;                 else if constexpr (L == 2) { F.ids(); convert_mats(F, 29, 32, ci * NWAVES + F.wave, nidle * NWAVES); }
;             } else if (nidle == 0) {
;                 if constexpr (L == 0) {
;                     pg8::Gemm g2{(const bf16*)(ws + WS_PB), (const bf16*)(ws + WS_WPP), M, 4 * D, PLE, (size_t)M * PLE * 2, 8, 1 << 30};
;                     pg8::StaticOrder S2; S2.init(M, 4 * D, F.G, bid);
;                     pg8::EpiScaleBf16<false> E2{(bf16*)(ws + WS_PPO), D, nullptr, D, (size_t)M * D, nullptr};
;                     pg8::gemm_phase<pg8::EpiScaleBf16<false>, pg8::StaticOrder, false, true>(F.lds, g2, S2, E2, F.wave);
;                 } else if constexpr (L == 1) { F.ids(); convert_mats(F, 27, 29, bid * NWAVES + F.wave, F.G * NWAVES); }
;                 else if constexpr (L == 2) { F.ids(); convert_mats(F, 29, 32, bid * NWAVES + F.wave, F.G * NWAVES); }
;             }
.LBB0_2066:
	s_andn2_b64 vcc, exec, s[0:1]
	s_cbranch_vccnz .LBB0_2182
	v_mbcnt_lo_u32_b32 v182, -1, 0
	v_mbcnt_hi_u32_b32 v182, -1, v182
	v_lshrrev_b32_e32 v183, 3, v182
	v_and_b32_e32 v184, 7, v182
	s_lshl_b32 s4, s80, 14
	v_mul_u32_u24_e32 v0, 132, v183
	v_lshl_add_u32 v0, v184, 4, v0
	v_add_u32_e32 v172, s4, v0
	v_add_u32_e32 v173, 0x420, v172
	v_add_u32_e32 v174, 0x840, v172
	v_add_u32_e32 v175, 0xc60, v172
	v_add_u32_e32 v176, 0x1080, v172
	v_add_u32_e32 v177, 0x14a0, v172
	v_add_u32_e32 v178, 0x18c0, v172
	v_add_u32_e32 v179, 0x1ce0, v172
	v_mul_u32_u24_e32 v0, 0x420, v184
	v_lshl_add_u32 v0, v183, 2, v0
	v_add_u32_e32 v180, s4, v0
	v_lshlrev_b32_e32 v181, 2, v183
	s_lshl_b32 s20, s33, 3
	s_add_u32 s20, s20, s80
	s_lshl_b32 s21, s3, 3
	s_mov_b32 s22, 0
	s_add_i32 s4, 0, 0x20520
	v_mov_b32_e32 v0, s4
	ds_read_b64 v[2:3], v0
	s_waitcnt lgkmcnt(0)
	s_nop 0
	v_readfirstlane_b32 s58, v2
	v_readfirstlane_b32 s59, v3
	s_add_u32 s23, s22, 0xb00
	s_cmp_ge_u32 s20, s23
	s_cbranch_scc1 .Lcvc_m25_done
	s_add_i32 s4, 0, 0x204f0
	v_mov_b32_e32 v0, s4
	ds_read_b64 v[2:3], v0
	s_waitcnt lgkmcnt(0)
	s_nop 0
	v_readfirstlane_b32 s24, v2
	v_readfirstlane_b32 s25, v3
	s_add_u32 s24, s24, 0x5800000
	s_addc_u32 s25, s25, 0
	s_add_u32 s28, s58, 0x1c300000
	s_addc_u32 s29, s59, 0
	s_mov_b32 s30, 0x2000
	s_mov_b32 s31, 0x2c00
	s_mov_b32 s34, 0x8000000
	s_mov_b32 s35, 32
	s_mov_b32 s36, 0
	v_mul_lo_u32 v0, v183, s30
	v_lshl_add_u32 v160, v184, 4, v0
	v_add_u32_e32 v161, 0x10000, v160
	v_add_u32_e32 v162, 0x20000, v160
	v_add_u32_e32 v163, 0x30000, v160
	v_add_u32_e32 v164, 0x40000, v160
	v_add_u32_e32 v165, 0x50000, v160
	v_add_u32_e32 v166, 0x60000, v160
	v_add_u32_e32 v167, 0x70000, v160
	v_mul_lo_u32 v0, v183, s31
	v_lshl_add_u32 v168, v184, 4, v0
	v_add_u32_e32 v169, 0x16000, v168
	v_add_u32_e32 v170, 0x2c000, v168
	v_add_u32_e32 v171, 0x42000, v168

; #define LAS __attribute__((address_space(3)))
; __device__ __forceinline__ void convert_mats(Frame& F, int m_lo, int m_hi, int gw, int NGW) {
;     LAS float* scr = (LAS float*)(F.lds + F.wave * 16384);
;     int it = gw, base = 0;
;     for (int mi = m_lo; mi < m_hi; ++mi) {
;         const MatI mt = kMats[mi]; const int cnt = (mt.Kp / 64) * (mt.Np / 64);
;         const float* src = in_ptr(F, mt.in_idx) + mt.src_off; const float* gain = mt.gain_idx >= 0 ? in_ptr(F, mt.gain_idx) + mt.gain_off : nullptr; bf16* dst = (bf16*)((unsigned char*)in_ptr(F, T_WS) + mt.dst_off);
;         while (it < base + cnt) {
.Lcvc_m25_done:
	s_mov_b32 s22, s23
	s_add_u32 s23, s22, 0x400
	s_cmp_ge_u32 s20, s23
	s_cbranch_scc1 .Lcvc_m26_done
	s_add_i32 s4, 0, 0x20508
	v_mov_b32_e32 v0, s4
	ds_read_b64 v[2:3], v0
	s_waitcnt lgkmcnt(0)
	s_nop 0
	v_readfirstlane_b32 s24, v2
	v_readfirstlane_b32 s25, v3
	s_add_u32 s24, s24, 0x2000000
	s_addc_u32 s25, s25, 0
	s_add_i32 s4, 0, 0x20500
	v_mov_b32_e32 v0, s4
	ds_read_b64 v[2:3], v0
	s_waitcnt lgkmcnt(0)
	s_nop 0
	v_readfirstlane_b32 s26, v2
	v_readfirstlane_b32 s27, v3
	s_add_u32 s26, s26, 0x4000
	s_addc_u32 s27, s27, 0
	s_add_u32 s28, s58, 0x1ff00000
	s_addc_u32 s29, s59, 0
	s_mov_b32 s30, 0x2000
	s_mov_b32 s31, 0x1000
	s_mov_b32 s34, 0x8000000
	s_mov_b32 s35, 32
	s_mov_b32 s36, 0
	v_mul_lo_u32 v0, v183, s30
	v_lshl_add_u32 v160, v184, 4, v0
	v_add_u32_e32 v161, 0x10000, v160
	v_add_u32_e32 v162, 0x20000, v160
	v_add_u32_e32 v163, 0x30000, v160
	v_add_u32_e32 v164, 0x40000, v160
	v_add_u32_e32 v165, 0x50000, v160
	v_add_u32_e32 v166, 0x60000, v160
	v_add_u32_e32 v167, 0x70000, v160
	v_mul_lo_u32 v0, v183, s31
	v_lshl_add_u32 v168, v184, 4, v0
	v_add_u32_e32 v169, 0x8000, v168
	v_add_u32_e32 v170, 0x10000, v168
	v_add_u32_e32 v171, 0x18000, v168

; #define LAS __attribute__((address_space(3)))
; __device__ __forceinline__ void convert_mats(Frame& F, int m_lo, int m_hi, int gw, int NGW) {
;     LAS float* scr = (LAS float*)(F.lds + F.wave * 16384);
;     int it = gw, base = 0;
;     for (int mi = m_lo; mi < m_hi; ++mi) {
;         const MatI mt = kMats[mi]; const int cnt = (mt.Kp / 64) * (mt.Np / 64);
;         const float* src = in_ptr(F, mt.in_idx) + mt.src_off; const float* gain = mt.gain_idx >= 0 ? in_ptr(F, mt.gain_idx) + mt.gain_off : nullptr; bf16* dst = (bf16*)((unsigned char*)in_ptr(F, T_WS) + mt.dst_off);
;         while (it < base + cnt) {
.Lcvc_m26_done:
	s_mov_b32 s22, s23
	s_add_u32 s23, s22, 0xb00
	s_cmp_ge_u32 s20, s23
	s_cbranch_scc1 .Lcvc_m30_done
	s_add_i32 s4, 0, 0x204f0
	v_mov_b32_e32 v0, s4
	ds_read_b64 v[2:3], v0
	s_waitcnt lgkmcnt(0)
	s_nop 0
	v_readfirstlane_b32 s24, v2
	v_readfirstlane_b32 s25, v3
	s_add_u32 s24, s24, 0x8400000
	s_addc_u32 s25, s25, 0
	s_add_u32 s28, s58, 0x1d900000
	s_addc_u32 s29, s59, 0
	s_mov_b32 s30, 0x2000
	s_mov_b32 s31, 0x2c00
	s_mov_b32 s34, 0x8000000
	s_mov_b32 s35, 32
	s_mov_b32 s36, 0
	v_mul_lo_u32 v0, v183, s30
	v_lshl_add_u32 v160, v184, 4, v0
	v_add_u32_e32 v161, 0x10000, v160
	v_add_u32_e32 v162, 0x20000, v160
	v_add_u32_e32 v163, 0x30000, v160
	v_add_u32_e32 v164, 0x40000, v160
	v_add_u32_e32 v165, 0x50000, v160
	v_add_u32_e32 v166, 0x60000, v160
	v_add_u32_e32 v167, 0x70000, v160
	v_mul_lo_u32 v0, v183, s31
	v_lshl_add_u32 v168, v184, 4, v0
	v_add_u32_e32 v169, 0x16000, v168
	v_add_u32_e32 v170, 0x2c000, v168
	v_add_u32_e32 v171, 0x42000, v168

; __device__ __forceinline__ void convert_mats(Frame& F, int m_lo, int m_hi, int gw, int NGW) {
;     LAS float* scr = (LAS float*)(F.lds + F.wave * 16384);
;     int it = gw, base = 0;
;     for (int mi = m_lo; mi < m_hi; ++mi) {
;         const MatI mt = kMats[mi]; const int cnt = (mt.Kp / 64) * (mt.Np / 64);
;         const float* src = in_ptr(F, mt.in_idx) + mt.src_off; const float* gain = mt.gain_idx >= 0 ? in_ptr(F, mt.gain_idx) + mt.gain_off : nullptr; bf16* dst = (bf16*)((unsigned char*)in_ptr(F, T_WS) + mt.dst_off);
; template <int L> __device__ __forceinline__ void layer_phases(Frame& F, const int lo, const int hi, const XcdBarrier& bar, const int bid) {
;     ...
;         {
;             const int rem = (M / 256) * (2 * FF / 256) % F.G, nidle = rem ? F.G - rem : 0, ci = bid - rem;
;             if (nidle > 0 && ci >= 0) {
;                 if constexpr (L == 0) {
;                     pg8::Gemm g2{(const bf16*)(ws + WS_PB), (const bf16*)(ws + WS_WPP), M, 4 * D, PLE, (size_t)M * PLE * 2, 8, 1 << 30};
;                     pg8::StaticOrder S2; S2.init(M, 4 * D, nidle, ci);
;                     pg8::EpiScaleBf16<false> E2{(bf16*)(ws + WS_PPO), D, nullptr, D, (size_t)M * D, nullptr};
;                     pg8::gemm_phase<pg8::EpiScaleBf16<false>, pg8::StaticOrder, false, true>(F.lds, g2, S2, E2, F.wave);
;                 } else if constexpr (L == 1) { F.ids(); convert_mats(F, 27, 29, ci * NWAVES + F.wave, nidle * NWAVES); }
;                 else if constexpr (L == 2) { F.ids(); convert_mats(F, 29, 32, ci * NWAVES + F.wave, nidle * NWAVES); }
;             } else if (nidle == 0) {
;                 if constexpr (L == 0) {
;                     pg8::Gemm g2{(const bf16*)(ws + WS_PB), (const bf16*)(ws + WS_WPP), M, 4 * D, PLE, (size_t)M * PLE * 2, 8, 1 << 30};
;                     pg8::StaticOrder S2; S2.init(M, 4 * D, F.G, bid);
;                     pg8::EpiScaleBf16<false> E2{(bf16*)(ws + WS_PPO), D, nullptr, D, (size_t)M * D, nullptr};
;                     pg8::gemm_phase<pg8::EpiScaleBf16<false>, pg8::StaticOrder, false, true>(F.lds, g2, S2, E2, F.wave);
;                 } else if constexpr (L == 1) { F.ids(); convert_mats(F, 27, 29, bid * NWAVES + F.wave, F.G * NWAVES); }
;                 else if constexpr (L == 2) { F.ids(); convert_mats(F, 29, 32, bid * NWAVES + F.wave, F.G * NWAVES); }
;             }
;         }
;         SEAM(pb + 6);
.LBB0_2842:
	s_andn2_b64 vcc, exec, s[0:1]
	s_cbranch_vccnz .LBB0_2958
	v_mbcnt_lo_u32_b32 v182, -1, 0
	v_mbcnt_hi_u32_b32 v182, -1, v182
	v_lshrrev_b32_e32 v183, 3, v182
	v_and_b32_e32 v184, 7, v182
	s_lshl_b32 s4, s80, 14
	v_mul_u32_u24_e32 v0, 132, v183
	v_lshl_add_u32 v0, v184, 4, v0
	v_add_u32_e32 v172, s4, v0
	v_add_u32_e32 v173, 0x420, v172
	v_add_u32_e32 v174, 0x840, v172
	v_add_u32_e32 v175, 0xc60, v172
	v_add_u32_e32 v176, 0x1080, v172
	v_add_u32_e32 v177, 0x14a0, v172
	v_add_u32_e32 v178, 0x18c0, v172
	v_add_u32_e32 v179, 0x1ce0, v172
	v_mul_u32_u24_e32 v0, 0x420, v184
	v_lshl_add_u32 v0, v183, 2, v0
	v_add_u32_e32 v180, s4, v0
	v_lshlrev_b32_e32 v181, 2, v183
	s_lshl_b32 s20, s33, 3
	s_add_u32 s20, s20, s80
	s_lshl_b32 s21, s3, 3
	s_mov_b32 s22, 0
	s_add_i32 s4, 0, 0x20520
	v_mov_b32_e32 v0, s4
	ds_read_b64 v[2:3], v0
	s_waitcnt lgkmcnt(0)
	s_nop 0
	v_readfirstlane_b32 s58, v2
	v_readfirstlane_b32 s59, v3
	s_add_u32 s23, s22, 0x1600
	s_cmp_ge_u32 s20, s23
	s_cbranch_scc1 .Lcvd_m29_done
	s_add_i32 s4, 0, 0x204d8
	v_mov_b32_e32 v0, s4
	ds_read_b64 v[2:3], v0
	s_waitcnt lgkmcnt(0)
	s_nop 0
	v_readfirstlane_b32 s24, v2
	v_readfirstlane_b32 s25, v3
	s_add_u32 s24, s24, 0x10800000
	s_addc_u32 s25, s25, 0
	s_add_i32 s4, 0, 0x204d0
	v_mov_b32_e32 v0, s4
	ds_read_b64 v[2:3], v0
	s_waitcnt lgkmcnt(0)
	s_nop 0
	v_readfirstlane_b32 s26, v2
	v_readfirstlane_b32 s27, v3
	s_add_u32 s26, s26, 0x6000
	s_addc_u32 s27, s27, 0
	s_add_u32 s28, s58, 0x16b00000
	s_addc_u32 s29, s59, 0
	s_mov_b32 s30, 0xb000
	s_mov_b32 s31, 0x1000
	s_mov_b32 s34, 0x1745d18
	s_mov_b32 s35, 176
	s_mov_b32 s36, 5632
	v_mul_lo_u32 v0, v183, s30
	v_lshl_add_u32 v160, v184, 4, v0
	v_add_u32_e32 v161, 0x58000, v160
	v_add_u32_e32 v162, 0xb0000, v160
	v_add_u32_e32 v163, 0x108000, v160
	v_add_u32_e32 v164, 0x160000, v160
	v_add_u32_e32 v165, 0x1b8000, v160
	v_add_u32_e32 v166, 0x210000, v160
	v_add_u32_e32 v167, 0x268000, v160
	v_mul_lo_u32 v0, v183, s31
	v_lshl_add_u32 v168, v184, 4, v0
	v_add_u32_e32 v169, 0x8000, v168
	v_add_u32_e32 v170, 0x10000, v168
	v_add_u32_e32 v171, 0x18000, v168

; #define LAS __attribute__((address_space(3)))
; __device__ __forceinline__ void convert_mats(Frame& F, int m_lo, int m_hi, int gw, int NGW) {
;     LAS float* scr = (LAS float*)(F.lds + F.wave * 16384);
;     int it = gw, base = 0;
;     for (int mi = m_lo; mi < m_hi; ++mi) {
;         const MatI mt = kMats[mi]; const int cnt = (mt.Kp / 64) * (mt.Np / 64);
;         const float* src = in_ptr(F, mt.in_idx) + mt.src_off; const float* gain = mt.gain_idx >= 0 ? in_ptr(F, mt.gain_idx) + mt.gain_off : nullptr; bf16* dst = (bf16*)((unsigned char*)in_ptr(F, T_WS) + mt.dst_off);
;         while (it < base + cnt) {
.Lcvd_m29_done:
	s_mov_b32 s22, s23
	s_add_u32 s23, s22, 0x400
	s_cmp_ge_u32 s20, s23
	s_cbranch_scc1 .Lcvd_m31_done
	s_add_i32 s4, 0, 0x20508
	v_mov_b32_e32 v0, s4
	ds_read_b64 v[2:3], v0
	s_waitcnt lgkmcnt(0)
	s_nop 0
	v_readfirstlane_b32 s24, v2
	v_readfirstlane_b32 s25, v3
	s_add_u32 s24, s24, 0x3000000
	s_addc_u32 s25, s25, 0
	s_add_i32 s4, 0, 0x20500
	v_mov_b32_e32 v0, s4
	ds_read_b64 v[2:3], v0
	s_waitcnt lgkmcnt(0)
	s_nop 0
	v_readfirstlane_b32 s26, v2
	v_readfirstlane_b32 s27, v3
	s_add_u32 s26, s26, 0x6000
	s_addc_u32 s27, s27, 0
	s_add_u32 s28, s58, 0x20700000
	s_addc_u32 s29, s59, 0
	s_mov_b32 s30, 0x2000
	s_mov_b32 s31, 0x1000
	s_mov_b32 s34, 0x8000000
	s_mov_b32 s35, 32
	s_mov_b32 s36, 0
	v_mul_lo_u32 v0, v183, s30
	v_lshl_add_u32 v160, v184, 4, v0
	v_add_u32_e32 v161, 0x10000, v160
	v_add_u32_e32 v162, 0x20000, v160
	v_add_u32_e32 v163, 0x30000, v160
	v_add_u32_e32 v164, 0x40000, v160
	v_add_u32_e32 v165, 0x50000, v160
	v_add_u32_e32 v166, 0x60000, v160
	v_add_u32_e32 v167, 0x70000, v160
	v_mul_lo_u32 v0, v183, s31
	v_lshl_add_u32 v168, v184, 4, v0
	v_add_u32_e32 v169, 0x8000, v168
	v_add_u32_e32 v170, 0x10000, v168
	v_add_u32_e32 v171, 0x18000, v168
